# scan rewrite: C-state scan coefficients precomputed, 32 chunk loads in flight, nst loads up front
# baseline (speedup 1.0000x reference)
; __device__ __forceinline__ void phase_scan(bf16_t* Cst, float* nst, const float* gch, const float* mloc, float* mprev) {
;     ...
;     for (int i = blockIdx.x * NTHR + tid; i < NBH * 8192 + NBH * 256; i += gridDim.x * NTHR) {
;         if (i < NBH * 8192) {
;             const int bh = i >> 13, e8 = i & 8191;
;             float st[8];
; #pragma unroll
;             for (int e = 0; e < 8; ++e) st[e] = 0.f;
;             float m = -1e30f;
;             for (int c0 = 0; c0 < 32; c0 += 8) {
;                 u32x4 ld[8];
; #pragma unroll
;                 for (int j = 0; j < 8; ++j) ld[j] = *(const u32x4*)(Cst + ((size_t)(bh * 32 + c0 + j) * 65536 + e8 * 8));
; #pragma unroll
;                 for (int j = 0; j < 8; ++j) { const int c = c0 + j; const float gc = gch[bh * 32 + c], mc = mloc[bh * 32 + c];
;                     const float mn = fmaxf(gc + m, mc), aa = __expf(gc + m - mn), bb = __expf(mc - mn);
;                     float lc[8]; unpack8(ld[j], lc);
;                     *(u32x4*)(Cst + ((size_t)(bh * 32 + c) * 65536 + e8 * 8)) = pack8(st);
; #pragma unroll
;                     for (int e = 0; e < 8; ++e) st[e] = aa * st[e] + bb * lc[e];
;                     if (e8 == 0) mprev[bh * 32 + c] = m;
;                     m = mn; }
;             }
;         } else {
;             const int j = i - NBH * 8192, bh = j >> 8, k = j & 255;
;             float st = 0.f, m = -1e30f;
;             for (int c = 0; c < 32; ++c) { const float gc = gch[bh * 32 + c], mc = mloc[bh * 32 + c];
;                 const float mn = fmaxf(gc + m, mc), aa = __expf(gc + m - mn), bb = __expf(mc - mn);
;                 const size_t o = (size_t)(bh * 32 + c) * 256 + k; const float lc = nst[o]; nst[o] = st; st = aa * st + bb * lc; m = mn; }
;         }
.LBB0_208:
	s_andn2_b64 vcc, exec, s[0:1]
	s_cbranch_vccnz .LBB0_260
	v_mov_b32_e32 v0, v194
	v_readlane_b32 s0, v254, 23
	s_nop 1
	v_add_u32_e32 v249, s0, v0
	s_mov_b32 s0, 0x21000
	v_cmp_gt_i32_e32 vcc, s0, v249
	s_and_saveexec_b64 s[0:1], vcc
	s_mov_b32 s13, 0x1ffff
	s_mov_b64 s[16:17], 0x1000
	s_cbranch_execz .LBB0_234
	v_readlane_b32 s4, v254, 24
	v_and_b32_e32 v248, 0xff, v0
	v_lshlrev_b32_e32 v248, 2, v248
	v_add_u32_e32 v250, s4, v0
	v_readlane_b32 s4, v254, 23
	s_mov_b64 s[6:7], 0
	s_nop 0
	v_add_u32_e32 v251, s4, v0
	s_add_u32 s98, s90, 0x3080000
	s_addc_u32 s99, s91, 0
	s_mov_b32 s100, 0x20000
	s_mov_b32 s101, 0
	s_branch .LBB0_212
.LBB0_211:
	s_or_b64 exec, exec, s[8:9]
	v_add_u32_e32 v249, s61, v249
	s_mov_b32 s4, 0x20fff
	v_cmp_lt_i32_e32 vcc, s4, v249
	v_add_u32_e32 v250, s61, v250
	s_or_b64 s[6:7], vcc, s[6:7]
	v_add_u32_e32 v251, s61, v251
	s_andn2_b64 exec, exec, s[6:7]
	s_cbranch_execz .LBB0_234
.LBB0_212:
	v_cmp_lt_i32_e32 vcc, s13, v249
	s_and_saveexec_b64 s[4:5], vcc
	s_xor_b64 s[4:5], exec, s[4:5]
	s_cbranch_execz .LBB0_215
	v_lshrrev_b32_e32 v0, 8, v250
	v_lshlrev_b64 v[2:3], 15, v[0:1]
	v_lshlrev_b32_e32 v0, 7, v0
	v_or_b32_e32 v2, v248, v2
	s_add_u32 s10, s90, 0x3100000
	s_addc_u32 s11, s91, 0
	v_lshl_add_u64 v[6:7], v[0:1], 0, s[98:99]
	v_lshl_add_u64 v[160:161], v[2:3], 0, s[10:11]
	global_load_dwordx4 v[64:67], v[6:7], off offset:0
	global_load_dwordx4 v[68:71], v[6:7], off offset:16
	global_load_dwordx4 v[72:75], v[6:7], off offset:32
	global_load_dwordx4 v[76:79], v[6:7], off offset:48
	global_load_dwordx4 v[80:83], v[6:7], off offset:64
	global_load_dwordx4 v[84:87], v[6:7], off offset:80
	global_load_dwordx4 v[88:91], v[6:7], off offset:96
	global_load_dwordx4 v[92:95], v[6:7], off offset:112
	global_load_dwordx4 v[96:99], v[6:7], off offset:2048
	global_load_dwordx4 v[100:103], v[6:7], off offset:2064
	global_load_dwordx4 v[104:107], v[6:7], off offset:2080
	global_load_dwordx4 v[108:111], v[6:7], off offset:2096
	global_load_dwordx4 v[112:115], v[6:7], off offset:2112
	global_load_dwordx4 v[116:119], v[6:7], off offset:2128
	global_load_dwordx4 v[120:123], v[6:7], off offset:2144
	global_load_dwordx4 v[124:127], v[6:7], off offset:2160
	global_load_dword v128, v[160:161], off
	global_load_dword v129, v[160:161], off offset:1024
	global_load_dword v130, v[160:161], off offset:2048
	global_load_dword v131, v[160:161], off offset:3072
	v_lshl_add_u64 v[162:163], v[160:161], 0, s[16:17]
	global_load_dword v132, v[162:163], off
	global_load_dword v133, v[162:163], off offset:1024
	global_load_dword v134, v[162:163], off offset:2048
	global_load_dword v135, v[162:163], off offset:3072
	v_lshl_add_u64 v[164:165], v[162:163], 0, s[16:17]
	global_load_dword v136, v[164:165], off
	global_load_dword v137, v[164:165], off offset:1024
	global_load_dword v138, v[164:165], off offset:2048
	global_load_dword v139, v[164:165], off offset:3072
	v_lshl_add_u64 v[166:167], v[164:165], 0, s[16:17]
	global_load_dword v140, v[166:167], off
	global_load_dword v141, v[166:167], off offset:1024
	global_load_dword v142, v[166:167], off offset:2048
	global_load_dword v143, v[166:167], off offset:3072
	v_lshl_add_u64 v[168:169], v[166:167], 0, s[16:17]
	global_load_dword v144, v[168:169], off
	global_load_dword v145, v[168:169], off offset:1024
	global_load_dword v146, v[168:169], off offset:2048
	global_load_dword v147, v[168:169], off offset:3072
	v_lshl_add_u64 v[170:171], v[168:169], 0, s[16:17]
	global_load_dword v148, v[170:171], off
	global_load_dword v149, v[170:171], off offset:1024
	global_load_dword v150, v[170:171], off offset:2048
	global_load_dword v151, v[170:171], off offset:3072
	v_lshl_add_u64 v[172:173], v[170:171], 0, s[16:17]
	global_load_dword v152, v[172:173], off
	global_load_dword v153, v[172:173], off offset:1024
	global_load_dword v154, v[172:173], off offset:2048
	global_load_dword v155, v[172:173], off offset:3072
	v_lshl_add_u64 v[174:175], v[172:173], 0, s[16:17]
	global_load_dword v156, v[174:175], off
	global_load_dword v157, v[174:175], off offset:1024
	global_load_dword v158, v[174:175], off offset:2048
	global_load_dword v159, v[174:175], off offset:3072
	v_mov_b32_e32 v10, 0
	v_mov_b32_e32 v11, 0xf149f2ca
	s_waitcnt vmcnt(31)
	v_add_f32_e32 v0, v11, v64
	v_max_f32_e32 v9, v96, v96
	v_max_f32_e32 v11, v0, v9
	v_sub_f32_e32 v8, v96, v11
	v_mul_f32_e32 v8, 0x3fb8aa3b, v8
	v_exp_f32_e32 v12, v8
	v_sub_f32_e32 v0, v0, v11
	v_mul_f32_e32 v0, 0x3fb8aa3b, v0
	v_exp_f32_e32 v0, v0
	global_store_dword v[160:161], v10, off
	v_mul_f32_e32 v12, v128, v12
	s_nop 0
	v_fmac_f32_e32 v12, v10, v0
	v_mov_b32_e32 v10, v12
	s_waitcnt vmcnt(31)
	v_add_f32_e32 v0, v11, v65
	v_max_f32_e32 v9, v97, v97
	v_max_f32_e32 v11, v0, v9
	v_sub_f32_e32 v8, v97, v11
	v_mul_f32_e32 v8, 0x3fb8aa3b, v8
	v_exp_f32_e32 v12, v8
	v_sub_f32_e32 v0, v0, v11
	v_mul_f32_e32 v0, 0x3fb8aa3b, v0
	v_exp_f32_e32 v0, v0
	global_store_dword v[160:161], v10, off offset:1024
	v_mul_f32_e32 v12, v129, v12
	s_nop 0
	v_fmac_f32_e32 v12, v10, v0
	v_mov_b32_e32 v10, v12
	s_waitcnt vmcnt(31)
	v_add_f32_e32 v0, v11, v66
	v_max_f32_e32 v9, v98, v98
	v_max_f32_e32 v11, v0, v9
	v_sub_f32_e32 v8, v98, v11
	v_mul_f32_e32 v8, 0x3fb8aa3b, v8
	v_exp_f32_e32 v12, v8
	v_sub_f32_e32 v0, v0, v11
	v_mul_f32_e32 v0, 0x3fb8aa3b, v0
	v_exp_f32_e32 v0, v0
	global_store_dword v[160:161], v10, off offset:2048
	v_mul_f32_e32 v12, v130, v12
	s_nop 0
	v_fmac_f32_e32 v12, v10, v0
	v_mov_b32_e32 v10, v12
	s_waitcnt vmcnt(31)
; __device__ __forceinline__ void phase_scan(bf16_t* Cst, float* nst, const float* gch, const float* mloc, float* mprev) {
;     ...
;             const int j = i - NBH * 8192, bh = j >> 8, k = j & 255;
;             float st = 0.f, m = -1e30f;
;             for (int c = 0; c < 32; ++c) { const float gc = gch[bh * 32 + c], mc = mloc[bh * 32 + c];
;                 const float mn = fmaxf(gc + m, mc), aa = __expf(gc + m - mn), bb = __expf(mc - mn);
;                 const size_t o = (size_t)(bh * 32 + c) * 256 + k; const float lc = nst[o]; nst[o] = st; st = aa * st + bb * lc; m = mn; }
	v_add_f32_e32 v0, v11, v67
	v_max_f32_e32 v9, v99, v99
	v_max_f32_e32 v11, v0, v9
	v_sub_f32_e32 v8, v99, v11
	v_mul_f32_e32 v8, 0x3fb8aa3b, v8
	v_exp_f32_e32 v12, v8
	v_sub_f32_e32 v0, v0, v11
	v_mul_f32_e32 v0, 0x3fb8aa3b, v0
	v_exp_f32_e32 v0, v0
	global_store_dword v[160:161], v10, off offset:3072
	v_mul_f32_e32 v12, v131, v12
	s_nop 0
	v_fmac_f32_e32 v12, v10, v0
	v_mov_b32_e32 v10, v12
	s_waitcnt vmcnt(31)
	v_add_f32_e32 v0, v11, v68
	v_max_f32_e32 v9, v100, v100
	v_max_f32_e32 v11, v0, v9
	v_sub_f32_e32 v8, v100, v11
	v_mul_f32_e32 v8, 0x3fb8aa3b, v8
	v_exp_f32_e32 v12, v8
	v_sub_f32_e32 v0, v0, v11
	v_mul_f32_e32 v0, 0x3fb8aa3b, v0
	v_exp_f32_e32 v0, v0
	global_store_dword v[162:163], v10, off
	v_mul_f32_e32 v12, v132, v12
	s_nop 0
	v_fmac_f32_e32 v12, v10, v0
	v_mov_b32_e32 v10, v12
	s_waitcnt vmcnt(31)
	v_add_f32_e32 v0, v11, v69
	v_max_f32_e32 v9, v101, v101
	v_max_f32_e32 v11, v0, v9
	v_sub_f32_e32 v8, v101, v11
	v_mul_f32_e32 v8, 0x3fb8aa3b, v8
	v_exp_f32_e32 v12, v8
	v_sub_f32_e32 v0, v0, v11
	v_mul_f32_e32 v0, 0x3fb8aa3b, v0
	v_exp_f32_e32 v0, v0
	global_store_dword v[162:163], v10, off offset:1024
	v_mul_f32_e32 v12, v133, v12
	s_nop 0
	v_fmac_f32_e32 v12, v10, v0
	v_mov_b32_e32 v10, v12
	s_waitcnt vmcnt(31)
	v_add_f32_e32 v0, v11, v70
	v_max_f32_e32 v9, v102, v102
	v_max_f32_e32 v11, v0, v9
	v_sub_f32_e32 v8, v102, v11
	v_mul_f32_e32 v8, 0x3fb8aa3b, v8
	v_exp_f32_e32 v12, v8
	v_sub_f32_e32 v0, v0, v11
	v_mul_f32_e32 v0, 0x3fb8aa3b, v0
	v_exp_f32_e32 v0, v0
	global_store_dword v[162:163], v10, off offset:2048
	v_mul_f32_e32 v12, v134, v12
	s_nop 0
	v_fmac_f32_e32 v12, v10, v0
	v_mov_b32_e32 v10, v12
	s_waitcnt vmcnt(31)
	v_add_f32_e32 v0, v11, v71
	v_max_f32_e32 v9, v103, v103
	v_max_f32_e32 v11, v0, v9
	v_sub_f32_e32 v8, v103, v11
	v_mul_f32_e32 v8, 0x3fb8aa3b, v8
	v_exp_f32_e32 v12, v8
	v_sub_f32_e32 v0, v0, v11
	v_mul_f32_e32 v0, 0x3fb8aa3b, v0
	v_exp_f32_e32 v0, v0
	global_store_dword v[162:163], v10, off offset:3072
	v_mul_f32_e32 v12, v135, v12
	s_nop 0
	v_fmac_f32_e32 v12, v10, v0
	v_mov_b32_e32 v10, v12
	s_waitcnt vmcnt(31)
	v_add_f32_e32 v0, v11, v72
	v_max_f32_e32 v9, v104, v104
	v_max_f32_e32 v11, v0, v9
	v_sub_f32_e32 v8, v104, v11
	v_mul_f32_e32 v8, 0x3fb8aa3b, v8
	v_exp_f32_e32 v12, v8
	v_sub_f32_e32 v0, v0, v11
	v_mul_f32_e32 v0, 0x3fb8aa3b, v0
	v_exp_f32_e32 v0, v0
	global_store_dword v[164:165], v10, off
	v_mul_f32_e32 v12, v136, v12
	s_nop 0
	v_fmac_f32_e32 v12, v10, v0
	v_mov_b32_e32 v10, v12
	s_waitcnt vmcnt(31)
	v_add_f32_e32 v0, v11, v73
	v_max_f32_e32 v9, v105, v105
	v_max_f32_e32 v11, v0, v9
	v_sub_f32_e32 v8, v105, v11
	v_mul_f32_e32 v8, 0x3fb8aa3b, v8
	v_exp_f32_e32 v12, v8
	v_sub_f32_e32 v0, v0, v11
	v_mul_f32_e32 v0, 0x3fb8aa3b, v0
	v_exp_f32_e32 v0, v0
	global_store_dword v[164:165], v10, off offset:1024
	v_mul_f32_e32 v12, v137, v12
	s_nop 0
	v_fmac_f32_e32 v12, v10, v0
	v_mov_b32_e32 v10, v12
	s_waitcnt vmcnt(31)
	v_add_f32_e32 v0, v11, v74
	v_max_f32_e32 v9, v106, v106
	v_max_f32_e32 v11, v0, v9
	v_sub_f32_e32 v8, v106, v11
	v_mul_f32_e32 v8, 0x3fb8aa3b, v8
	v_exp_f32_e32 v12, v8
	v_sub_f32_e32 v0, v0, v11
	v_mul_f32_e32 v0, 0x3fb8aa3b, v0
	v_exp_f32_e32 v0, v0
	global_store_dword v[164:165], v10, off offset:2048
	v_mul_f32_e32 v12, v138, v12
	s_nop 0
	v_fmac_f32_e32 v12, v10, v0
	v_mov_b32_e32 v10, v12
	s_waitcnt vmcnt(31)
	v_add_f32_e32 v0, v11, v75
	v_max_f32_e32 v9, v107, v107
	v_max_f32_e32 v11, v0, v9
	v_sub_f32_e32 v8, v107, v11
	v_mul_f32_e32 v8, 0x3fb8aa3b, v8
	v_exp_f32_e32 v12, v8
	v_sub_f32_e32 v0, v0, v11
	v_mul_f32_e32 v0, 0x3fb8aa3b, v0
	v_exp_f32_e32 v0, v0
	global_store_dword v[164:165], v10, off offset:3072
	v_mul_f32_e32 v12, v139, v12
	s_nop 0
	v_fmac_f32_e32 v12, v10, v0
	v_mov_b32_e32 v10, v12
	s_waitcnt vmcnt(31)
	v_add_f32_e32 v0, v11, v76
	v_max_f32_e32 v9, v108, v108
	v_max_f32_e32 v11, v0, v9
	v_sub_f32_e32 v8, v108, v11
	v_mul_f32_e32 v8, 0x3fb8aa3b, v8
	v_exp_f32_e32 v12, v8
	v_sub_f32_e32 v0, v0, v11
	v_mul_f32_e32 v0, 0x3fb8aa3b, v0
	v_exp_f32_e32 v0, v0
	global_store_dword v[166:167], v10, off
	v_mul_f32_e32 v12, v140, v12
	s_nop 0
	v_fmac_f32_e32 v12, v10, v0
	v_mov_b32_e32 v10, v12
	s_waitcnt vmcnt(31)
	v_add_f32_e32 v0, v11, v77
	v_max_f32_e32 v9, v109, v109
	v_max_f32_e32 v11, v0, v9
	v_sub_f32_e32 v8, v109, v11
	v_mul_f32_e32 v8, 0x3fb8aa3b, v8
	v_exp_f32_e32 v12, v8
	v_sub_f32_e32 v0, v0, v11
	v_mul_f32_e32 v0, 0x3fb8aa3b, v0
	v_exp_f32_e32 v0, v0
	global_store_dword v[166:167], v10, off offset:1024
	v_mul_f32_e32 v12, v141, v12
	s_nop 0
	v_fmac_f32_e32 v12, v10, v0
	v_mov_b32_e32 v10, v12
	s_waitcnt vmcnt(31)
	v_add_f32_e32 v0, v11, v78
	v_max_f32_e32 v9, v110, v110
	v_max_f32_e32 v11, v0, v9
	v_sub_f32_e32 v8, v110, v11
	v_mul_f32_e32 v8, 0x3fb8aa3b, v8
	v_exp_f32_e32 v12, v8
	v_sub_f32_e32 v0, v0, v11
	v_mul_f32_e32 v0, 0x3fb8aa3b, v0
	v_exp_f32_e32 v0, v0
	global_store_dword v[166:167], v10, off offset:2048
	v_mul_f32_e32 v12, v142, v12
	s_nop 0
	v_fmac_f32_e32 v12, v10, v0
	v_mov_b32_e32 v10, v12
	s_waitcnt vmcnt(31)
	v_add_f32_e32 v0, v11, v79
	v_max_f32_e32 v9, v111, v111
	v_max_f32_e32 v11, v0, v9
	v_sub_f32_e32 v8, v111, v11
	v_mul_f32_e32 v8, 0x3fb8aa3b, v8
	v_exp_f32_e32 v12, v8
	v_sub_f32_e32 v0, v0, v11
	v_mul_f32_e32 v0, 0x3fb8aa3b, v0
	v_exp_f32_e32 v0, v0
	global_store_dword v[166:167], v10, off offset:3072
	v_mul_f32_e32 v12, v143, v12
	s_nop 0
	v_fmac_f32_e32 v12, v10, v0
	v_mov_b32_e32 v10, v12
	s_waitcnt vmcnt(31)
	v_add_f32_e32 v0, v11, v80
	v_max_f32_e32 v9, v112, v112
	v_max_f32_e32 v11, v0, v9
	v_sub_f32_e32 v8, v112, v11
	v_mul_f32_e32 v8, 0x3fb8aa3b, v8
	v_exp_f32_e32 v12, v8
	v_sub_f32_e32 v0, v0, v11
	v_mul_f32_e32 v0, 0x3fb8aa3b, v0
	v_exp_f32_e32 v0, v0
	global_store_dword v[168:169], v10, off
	v_mul_f32_e32 v12, v144, v12
	s_nop 0
	v_fmac_f32_e32 v12, v10, v0
	v_mov_b32_e32 v10, v12
	s_waitcnt vmcnt(31)
; __device__ __forceinline__ void phase_scan(bf16_t* Cst, float* nst, const float* gch, const float* mloc, float* mprev) {
;     ...
;             const int j = i - NBH * 8192, bh = j >> 8, k = j & 255;
;             float st = 0.f, m = -1e30f;
;             for (int c = 0; c < 32; ++c) { const float gc = gch[bh * 32 + c], mc = mloc[bh * 32 + c];
;                 const float mn = fmaxf(gc + m, mc), aa = __expf(gc + m - mn), bb = __expf(mc - mn);
;                 const size_t o = (size_t)(bh * 32 + c) * 256 + k; const float lc = nst[o]; nst[o] = st; st = aa * st + bb * lc; m = mn; }
	v_add_f32_e32 v0, v11, v81
	v_max_f32_e32 v9, v113, v113
	v_max_f32_e32 v11, v0, v9
	v_sub_f32_e32 v8, v113, v11
	v_mul_f32_e32 v8, 0x3fb8aa3b, v8
	v_exp_f32_e32 v12, v8
	v_sub_f32_e32 v0, v0, v11
	v_mul_f32_e32 v0, 0x3fb8aa3b, v0
	v_exp_f32_e32 v0, v0
	global_store_dword v[168:169], v10, off offset:1024
	v_mul_f32_e32 v12, v145, v12
	s_nop 0
	v_fmac_f32_e32 v12, v10, v0
	v_mov_b32_e32 v10, v12
	s_waitcnt vmcnt(31)
	v_add_f32_e32 v0, v11, v82
	v_max_f32_e32 v9, v114, v114
	v_max_f32_e32 v11, v0, v9
	v_sub_f32_e32 v8, v114, v11
	v_mul_f32_e32 v8, 0x3fb8aa3b, v8
	v_exp_f32_e32 v12, v8
	v_sub_f32_e32 v0, v0, v11
	v_mul_f32_e32 v0, 0x3fb8aa3b, v0
	v_exp_f32_e32 v0, v0
	global_store_dword v[168:169], v10, off offset:2048
	v_mul_f32_e32 v12, v146, v12
	s_nop 0
	v_fmac_f32_e32 v12, v10, v0
	v_mov_b32_e32 v10, v12
	s_waitcnt vmcnt(31)
	v_add_f32_e32 v0, v11, v83
	v_max_f32_e32 v9, v115, v115
	v_max_f32_e32 v11, v0, v9
	v_sub_f32_e32 v8, v115, v11
	v_mul_f32_e32 v8, 0x3fb8aa3b, v8
	v_exp_f32_e32 v12, v8
	v_sub_f32_e32 v0, v0, v11
	v_mul_f32_e32 v0, 0x3fb8aa3b, v0
	v_exp_f32_e32 v0, v0
	global_store_dword v[168:169], v10, off offset:3072
	v_mul_f32_e32 v12, v147, v12
	s_nop 0
	v_fmac_f32_e32 v12, v10, v0
	v_mov_b32_e32 v10, v12
	s_waitcnt vmcnt(31)
	v_add_f32_e32 v0, v11, v84
	v_max_f32_e32 v9, v116, v116
	v_max_f32_e32 v11, v0, v9
	v_sub_f32_e32 v8, v116, v11
	v_mul_f32_e32 v8, 0x3fb8aa3b, v8
	v_exp_f32_e32 v12, v8
	v_sub_f32_e32 v0, v0, v11
	v_mul_f32_e32 v0, 0x3fb8aa3b, v0
	v_exp_f32_e32 v0, v0
	global_store_dword v[170:171], v10, off
	v_mul_f32_e32 v12, v148, v12
	s_nop 0
	v_fmac_f32_e32 v12, v10, v0
	v_mov_b32_e32 v10, v12
	s_waitcnt vmcnt(31)
	v_add_f32_e32 v0, v11, v85
	v_max_f32_e32 v9, v117, v117
	v_max_f32_e32 v11, v0, v9
	v_sub_f32_e32 v8, v117, v11
	v_mul_f32_e32 v8, 0x3fb8aa3b, v8
	v_exp_f32_e32 v12, v8
	v_sub_f32_e32 v0, v0, v11
	v_mul_f32_e32 v0, 0x3fb8aa3b, v0
	v_exp_f32_e32 v0, v0
	global_store_dword v[170:171], v10, off offset:1024
	v_mul_f32_e32 v12, v149, v12
	s_nop 0
	v_fmac_f32_e32 v12, v10, v0
	v_mov_b32_e32 v10, v12
	s_waitcnt vmcnt(31)
	v_add_f32_e32 v0, v11, v86
	v_max_f32_e32 v9, v118, v118
	v_max_f32_e32 v11, v0, v9
	v_sub_f32_e32 v8, v118, v11
	v_mul_f32_e32 v8, 0x3fb8aa3b, v8
	v_exp_f32_e32 v12, v8
	v_sub_f32_e32 v0, v0, v11
	v_mul_f32_e32 v0, 0x3fb8aa3b, v0
	v_exp_f32_e32 v0, v0
	global_store_dword v[170:171], v10, off offset:2048
	v_mul_f32_e32 v12, v150, v12
	s_nop 0
	v_fmac_f32_e32 v12, v10, v0
	v_mov_b32_e32 v10, v12
	s_waitcnt vmcnt(31)
	v_add_f32_e32 v0, v11, v87
	v_max_f32_e32 v9, v119, v119
	v_max_f32_e32 v11, v0, v9
	v_sub_f32_e32 v8, v119, v11
	v_mul_f32_e32 v8, 0x3fb8aa3b, v8
	v_exp_f32_e32 v12, v8
	v_sub_f32_e32 v0, v0, v11
	v_mul_f32_e32 v0, 0x3fb8aa3b, v0
	v_exp_f32_e32 v0, v0
	global_store_dword v[170:171], v10, off offset:3072
	v_mul_f32_e32 v12, v151, v12
	s_nop 0
	v_fmac_f32_e32 v12, v10, v0
	v_mov_b32_e32 v10, v12
	s_waitcnt vmcnt(31)
	v_add_f32_e32 v0, v11, v88
	v_max_f32_e32 v9, v120, v120
	v_max_f32_e32 v11, v0, v9
	v_sub_f32_e32 v8, v120, v11
	v_mul_f32_e32 v8, 0x3fb8aa3b, v8
	v_exp_f32_e32 v12, v8
	v_sub_f32_e32 v0, v0, v11
	v_mul_f32_e32 v0, 0x3fb8aa3b, v0
	v_exp_f32_e32 v0, v0
	global_store_dword v[172:173], v10, off
	v_mul_f32_e32 v12, v152, v12
	s_nop 0
	v_fmac_f32_e32 v12, v10, v0
	v_mov_b32_e32 v10, v12
	s_waitcnt vmcnt(31)
	v_add_f32_e32 v0, v11, v89
	v_max_f32_e32 v9, v121, v121
	v_max_f32_e32 v11, v0, v9
	v_sub_f32_e32 v8, v121, v11
	v_mul_f32_e32 v8, 0x3fb8aa3b, v8
	v_exp_f32_e32 v12, v8
	v_sub_f32_e32 v0, v0, v11
	v_mul_f32_e32 v0, 0x3fb8aa3b, v0
	v_exp_f32_e32 v0, v0
	global_store_dword v[172:173], v10, off offset:1024
	v_mul_f32_e32 v12, v153, v12
	s_nop 0
	v_fmac_f32_e32 v12, v10, v0
	v_mov_b32_e32 v10, v12
	s_waitcnt vmcnt(31)
	v_add_f32_e32 v0, v11, v90
	v_max_f32_e32 v9, v122, v122
	v_max_f32_e32 v11, v0, v9
	v_sub_f32_e32 v8, v122, v11
	v_mul_f32_e32 v8, 0x3fb8aa3b, v8
	v_exp_f32_e32 v12, v8
	v_sub_f32_e32 v0, v0, v11
	v_mul_f32_e32 v0, 0x3fb8aa3b, v0
	v_exp_f32_e32 v0, v0
	global_store_dword v[172:173], v10, off offset:2048
	v_mul_f32_e32 v12, v154, v12
	s_nop 0
	v_fmac_f32_e32 v12, v10, v0
	v_mov_b32_e32 v10, v12
	s_waitcnt vmcnt(31)
	v_add_f32_e32 v0, v11, v91
	v_max_f32_e32 v9, v123, v123
	v_max_f32_e32 v11, v0, v9
	v_sub_f32_e32 v8, v123, v11
	v_mul_f32_e32 v8, 0x3fb8aa3b, v8
	v_exp_f32_e32 v12, v8
	v_sub_f32_e32 v0, v0, v11
	v_mul_f32_e32 v0, 0x3fb8aa3b, v0
	v_exp_f32_e32 v0, v0
	global_store_dword v[172:173], v10, off offset:3072
	v_mul_f32_e32 v12, v155, v12
	s_nop 0
	v_fmac_f32_e32 v12, v10, v0
	v_mov_b32_e32 v10, v12
	s_waitcnt vmcnt(31)
	v_add_f32_e32 v0, v11, v92
	v_max_f32_e32 v9, v124, v124
	v_max_f32_e32 v11, v0, v9
	v_sub_f32_e32 v8, v124, v11
	v_mul_f32_e32 v8, 0x3fb8aa3b, v8
	v_exp_f32_e32 v12, v8
	v_sub_f32_e32 v0, v0, v11
	v_mul_f32_e32 v0, 0x3fb8aa3b, v0
	v_exp_f32_e32 v0, v0
	global_store_dword v[174:175], v10, off
	v_mul_f32_e32 v12, v156, v12
	s_nop 0
	v_fmac_f32_e32 v12, v10, v0
	v_mov_b32_e32 v10, v12
	s_waitcnt vmcnt(31)
	v_add_f32_e32 v0, v11, v93
	v_max_f32_e32 v9, v125, v125
	v_max_f32_e32 v11, v0, v9
	v_sub_f32_e32 v8, v125, v11
	v_mul_f32_e32 v8, 0x3fb8aa3b, v8
	v_exp_f32_e32 v12, v8
	v_sub_f32_e32 v0, v0, v11
	v_mul_f32_e32 v0, 0x3fb8aa3b, v0
	v_exp_f32_e32 v0, v0
	global_store_dword v[174:175], v10, off offset:1024
	v_mul_f32_e32 v12, v157, v12
	s_nop 0
	v_fmac_f32_e32 v12, v10, v0
	v_mov_b32_e32 v10, v12
	s_waitcnt vmcnt(31)
	v_add_f32_e32 v0, v11, v94
	v_max_f32_e32 v9, v126, v126
	v_max_f32_e32 v11, v0, v9
	v_sub_f32_e32 v8, v126, v11
	v_mul_f32_e32 v8, 0x3fb8aa3b, v8
	v_exp_f32_e32 v12, v8
	v_sub_f32_e32 v0, v0, v11
	v_mul_f32_e32 v0, 0x3fb8aa3b, v0
	v_exp_f32_e32 v0, v0
	global_store_dword v[174:175], v10, off offset:2048
	v_mul_f32_e32 v12, v158, v12
	s_nop 0
	v_fmac_f32_e32 v12, v10, v0
	v_mov_b32_e32 v10, v12
	s_waitcnt vmcnt(31)
	v_add_f32_e32 v0, v11, v95
	v_max_f32_e32 v9, v127, v127
	v_max_f32_e32 v11, v0, v9
	v_sub_f32_e32 v8, v127, v11
	v_mul_f32_e32 v8, 0x3fb8aa3b, v8
	v_exp_f32_e32 v12, v8
	v_sub_f32_e32 v0, v0, v11
	v_mul_f32_e32 v0, 0x3fb8aa3b, v0
	v_exp_f32_e32 v0, v0
	global_store_dword v[174:175], v10, off offset:3072
	v_mul_f32_e32 v12, v159, v12
	s_nop 0
	v_fmac_f32_e32 v12, v10, v0
	v_mov_b32_e32 v10, v12
; __device__ __forceinline__ void phase_scan(bf16_t* Cst, float* nst, const float* gch, const float* mloc, float* mprev) {
;     ...
;         if (i < NBH * 8192) {
;             const int bh = i >> 13, e8 = i & 8191;
;             float st[8];
; #pragma unroll
;             for (int e = 0; e < 8; ++e) st[e] = 0.f;
;             float m = -1e30f;
;             for (int c0 = 0; c0 < 32; c0 += 8) {
;                 u32x4 ld[8];
; #pragma unroll
;                 for (int j = 0; j < 8; ++j) ld[j] = *(const u32x4*)(Cst + ((size_t)(bh * 32 + c0 + j) * 65536 + e8 * 8));
; #pragma unroll
;                 for (int j = 0; j < 8; ++j) { const int c = c0 + j; const float gc = gch[bh * 32 + c], mc = mloc[bh * 32 + c];
;                     const float mn = fmaxf(gc + m, mc), aa = __expf(gc + m - mn), bb = __expf(mc - mn);
;                     float lc[8]; unpack8(ld[j], lc);
;                     *(u32x4*)(Cst + ((size_t)(bh * 32 + c) * 65536 + e8 * 8)) = pack8(st);
; #pragma unroll
;                     for (int e = 0; e < 8; ++e) st[e] = aa * st[e] + bb * lc[e];
;                     if (e8 == 0) mprev[bh * 32 + c] = m;
;                     m = mn; }
.LBB0_215:
	s_andn2_saveexec_b64 s[8:9], s[4:5]
	s_cbranch_execz .LBB0_211
	v_ashrrev_i32_e32 v243, 8, v249
	v_and_b32_e32 v244, 0x1fff, v249
	v_and_b32_e32 v243, 0xffffffe0, v243
	v_cmp_eq_u32_e64 s[4:5], 0, v244
	v_lshlrev_b32_e32 v218, 2, v243
	v_mov_b32_e32 v219, 0
	v_lshl_add_u64 v[218:219], v[218:219], 0, s[98:99]
	global_load_dwordx4 v[2:5], v[218:219], off offset:0
	global_load_dwordx4 v[6:9], v[218:219], off offset:16
	global_load_dwordx4 v[10:13], v[218:219], off offset:32
	global_load_dwordx4 v[14:17], v[218:219], off offset:48
	global_load_dwordx4 v[18:21], v[218:219], off offset:64
	global_load_dwordx4 v[22:25], v[218:219], off offset:80
	global_load_dwordx4 v[26:29], v[218:219], off offset:96
	global_load_dwordx4 v[30:33], v[218:219], off offset:112
	global_load_dwordx4 v[34:37], v[218:219], off offset:2048
	global_load_dwordx4 v[38:41], v[218:219], off offset:2064
	global_load_dwordx4 v[42:45], v[218:219], off offset:2080
	global_load_dwordx4 v[46:49], v[218:219], off offset:2096
	global_load_dwordx4 v[50:53], v[218:219], off offset:2112
	global_load_dwordx4 v[54:57], v[218:219], off offset:2128
	global_load_dwordx4 v[58:61], v[218:219], off offset:2144
	global_load_dwordx4 v[62:65], v[218:219], off offset:2160
	v_mov_b32_e32 v245, 0
	v_mov_b32_e32 v246, v243
	v_mov_b32_e32 v247, 0
	v_lshlrev_b64 v[214:215], 17, v[246:247]
	v_lshl_or_b32 v214, v244, 4, v214
	s_add_u32 s10, s90, 0x5200000
	s_addc_u32 s11, s91, 0
	v_lshl_add_u64 v[214:215], v[214:215], 0, s[10:11]
	v_mov_b32_e32 v216, v214
	v_mov_b32_e32 v217, v215
	global_load_dwordx4 v[66:69], v[214:215], off
	v_lshl_add_u64 v[214:215], v[214:215], 0, s[100:101]
	global_load_dwordx4 v[70:73], v[214:215], off
	v_lshl_add_u64 v[214:215], v[214:215], 0, s[100:101]
	global_load_dwordx4 v[74:77], v[214:215], off
	v_lshl_add_u64 v[214:215], v[214:215], 0, s[100:101]
	global_load_dwordx4 v[78:81], v[214:215], off
	v_lshl_add_u64 v[214:215], v[214:215], 0, s[100:101]
	global_load_dwordx4 v[82:85], v[214:215], off
	v_lshl_add_u64 v[214:215], v[214:215], 0, s[100:101]
	global_load_dwordx4 v[86:89], v[214:215], off
	v_lshl_add_u64 v[214:215], v[214:215], 0, s[100:101]
	global_load_dwordx4 v[90:93], v[214:215], off
	v_lshl_add_u64 v[214:215], v[214:215], 0, s[100:101]
	global_load_dwordx4 v[94:97], v[214:215], off
	v_lshl_add_u64 v[214:215], v[214:215], 0, s[100:101]
	global_load_dwordx4 v[98:101], v[214:215], off
	v_lshl_add_u64 v[214:215], v[214:215], 0, s[100:101]
	global_load_dwordx4 v[102:105], v[214:215], off
	v_lshl_add_u64 v[214:215], v[214:215], 0, s[100:101]
	global_load_dwordx4 v[106:109], v[214:215], off
	v_lshl_add_u64 v[214:215], v[214:215], 0, s[100:101]
	global_load_dwordx4 v[110:113], v[214:215], off
	v_lshl_add_u64 v[214:215], v[214:215], 0, s[100:101]
	global_load_dwordx4 v[114:117], v[214:215], off
	v_lshl_add_u64 v[214:215], v[214:215], 0, s[100:101]
	global_load_dwordx4 v[118:121], v[214:215], off
	v_lshl_add_u64 v[214:215], v[214:215], 0, s[100:101]
	global_load_dwordx4 v[122:125], v[214:215], off
	v_lshl_add_u64 v[214:215], v[214:215], 0, s[100:101]
	global_load_dwordx4 v[126:129], v[214:215], off
	v_lshl_add_u64 v[214:215], v[214:215], 0, s[100:101]
	v_lshl_add_u64 v[238:239], v[218:219], 0, s[16:17]
	v_mov_b32_e32 v213, 0xf149f2ca
	v_mov_b32_e32 v205, 0
	v_mov_b32_e32 v206, 0
	v_mov_b32_e32 v207, 0
	v_mov_b32_e32 v208, 0
	v_mov_b32_e32 v209, 0
	v_mov_b32_e32 v210, 0
	v_mov_b32_e32 v211, 0
	v_mov_b32_e32 v212, 0
	s_waitcnt vmcnt(16)
	v_add_f32_e32 v240, v213, v2
	v_max_f32_e32 v241, v34, v34
	v_mov_b32_e32 v130, v213
	v_max_f32_e32 v213, v240, v241
	v_sub_f32_e32 v241, v34, v213
	v_sub_f32_e32 v240, v240, v213
	v_mul_f32_e32 v241, 0x3fb8aa3b, v241
	v_mul_f32_e32 v240, 0x3fb8aa3b, v240
	v_exp_f32_e32 v34, v241
	v_exp_f32_e32 v2, v240
	v_add_f32_e32 v240, v213, v3
	v_max_f32_e32 v241, v35, v35
	v_mov_b32_e32 v131, v213
	v_max_f32_e32 v213, v240, v241
	v_sub_f32_e32 v241, v35, v213
	v_sub_f32_e32 v240, v240, v213
	v_mul_f32_e32 v241, 0x3fb8aa3b, v241
	v_mul_f32_e32 v240, 0x3fb8aa3b, v240
	v_exp_f32_e32 v35, v241
	v_exp_f32_e32 v3, v240
	v_add_f32_e32 v240, v213, v4
	v_max_f32_e32 v241, v36, v36
	v_mov_b32_e32 v132, v213
	v_max_f32_e32 v213, v240, v241
	v_sub_f32_e32 v241, v36, v213
	v_sub_f32_e32 v240, v240, v213
	v_mul_f32_e32 v241, 0x3fb8aa3b, v241
	v_mul_f32_e32 v240, 0x3fb8aa3b, v240
	v_exp_f32_e32 v36, v241
	v_exp_f32_e32 v4, v240
	v_add_f32_e32 v240, v213, v5
	v_max_f32_e32 v241, v37, v37
	v_mov_b32_e32 v133, v213
	v_max_f32_e32 v213, v240, v241
	v_sub_f32_e32 v241, v37, v213
	v_sub_f32_e32 v240, v240, v213
	v_mul_f32_e32 v241, 0x3fb8aa3b, v241
	v_mul_f32_e32 v240, 0x3fb8aa3b, v240
	v_exp_f32_e32 v37, v241
	v_exp_f32_e32 v5, v240
	v_add_f32_e32 v240, v213, v6
	v_max_f32_e32 v241, v38, v38
	v_mov_b32_e32 v134, v213
	v_max_f32_e32 v213, v240, v241
	v_sub_f32_e32 v241, v38, v213
	v_sub_f32_e32 v240, v240, v213
	v_mul_f32_e32 v241, 0x3fb8aa3b, v241
	v_mul_f32_e32 v240, 0x3fb8aa3b, v240
	v_exp_f32_e32 v38, v241
	v_exp_f32_e32 v6, v240
	v_add_f32_e32 v240, v213, v7
	v_max_f32_e32 v241, v39, v39
	v_mov_b32_e32 v135, v213
	v_max_f32_e32 v213, v240, v241
	v_sub_f32_e32 v241, v39, v213
	v_sub_f32_e32 v240, v240, v213
	v_mul_f32_e32 v241, 0x3fb8aa3b, v241
	v_mul_f32_e32 v240, 0x3fb8aa3b, v240
	v_exp_f32_e32 v39, v241
	v_exp_f32_e32 v7, v240
	v_add_f32_e32 v240, v213, v8
	v_max_f32_e32 v241, v40, v40
	v_mov_b32_e32 v136, v213
	v_max_f32_e32 v213, v240, v241
	v_sub_f32_e32 v241, v40, v213
	v_sub_f32_e32 v240, v240, v213
	v_mul_f32_e32 v241, 0x3fb8aa3b, v241
	v_mul_f32_e32 v240, 0x3fb8aa3b, v240
	v_exp_f32_e32 v40, v241
	v_exp_f32_e32 v8, v240
	v_add_f32_e32 v240, v213, v9
; __device__ __forceinline__ void phase_scan(bf16_t* Cst, float* nst, const float* gch, const float* mloc, float* mprev) {
;     ...
;                 for (int j = 0; j < 8; ++j) { const int c = c0 + j; const float gc = gch[bh * 32 + c], mc = mloc[bh * 32 + c];
;                     const float mn = fmaxf(gc + m, mc), aa = __expf(gc + m - mn), bb = __expf(mc - mn);
;                     float lc[8]; unpack8(ld[j], lc);
;                     *(u32x4*)(Cst + ((size_t)(bh * 32 + c) * 65536 + e8 * 8)) = pack8(st);
; #pragma unroll
;                     for (int e = 0; e < 8; ++e) st[e] = aa * st[e] + bb * lc[e];
;                     if (e8 == 0) mprev[bh * 32 + c] = m;
	v_max_f32_e32 v241, v41, v41
	v_mov_b32_e32 v137, v213
	v_max_f32_e32 v213, v240, v241
	v_sub_f32_e32 v241, v41, v213
	v_sub_f32_e32 v240, v240, v213
	v_mul_f32_e32 v241, 0x3fb8aa3b, v241
	v_mul_f32_e32 v240, 0x3fb8aa3b, v240
	v_exp_f32_e32 v41, v241
	v_exp_f32_e32 v9, v240
	v_add_f32_e32 v240, v213, v10
	v_max_f32_e32 v241, v42, v42
	v_mov_b32_e32 v138, v213
	v_max_f32_e32 v213, v240, v241
	v_sub_f32_e32 v241, v42, v213
	v_sub_f32_e32 v240, v240, v213
	v_mul_f32_e32 v241, 0x3fb8aa3b, v241
	v_mul_f32_e32 v240, 0x3fb8aa3b, v240
	v_exp_f32_e32 v42, v241
	v_exp_f32_e32 v10, v240
	v_add_f32_e32 v240, v213, v11
	v_max_f32_e32 v241, v43, v43
	v_mov_b32_e32 v139, v213
	v_max_f32_e32 v213, v240, v241
	v_sub_f32_e32 v241, v43, v213
	v_sub_f32_e32 v240, v240, v213
	v_mul_f32_e32 v241, 0x3fb8aa3b, v241
	v_mul_f32_e32 v240, 0x3fb8aa3b, v240
	v_exp_f32_e32 v43, v241
	v_exp_f32_e32 v11, v240
	v_add_f32_e32 v240, v213, v12
	v_max_f32_e32 v241, v44, v44
	v_mov_b32_e32 v140, v213
	v_max_f32_e32 v213, v240, v241
	v_sub_f32_e32 v241, v44, v213
	v_sub_f32_e32 v240, v240, v213
	v_mul_f32_e32 v241, 0x3fb8aa3b, v241
	v_mul_f32_e32 v240, 0x3fb8aa3b, v240
	v_exp_f32_e32 v44, v241
	v_exp_f32_e32 v12, v240
	v_add_f32_e32 v240, v213, v13
	v_max_f32_e32 v241, v45, v45
	v_mov_b32_e32 v141, v213
	v_max_f32_e32 v213, v240, v241
	v_sub_f32_e32 v241, v45, v213
	v_sub_f32_e32 v240, v240, v213
	v_mul_f32_e32 v241, 0x3fb8aa3b, v241
	v_mul_f32_e32 v240, 0x3fb8aa3b, v240
	v_exp_f32_e32 v45, v241
	v_exp_f32_e32 v13, v240
	v_add_f32_e32 v240, v213, v14
	v_max_f32_e32 v241, v46, v46
	v_mov_b32_e32 v142, v213
	v_max_f32_e32 v213, v240, v241
	v_sub_f32_e32 v241, v46, v213
	v_sub_f32_e32 v240, v240, v213
	v_mul_f32_e32 v241, 0x3fb8aa3b, v241
	v_mul_f32_e32 v240, 0x3fb8aa3b, v240
	v_exp_f32_e32 v46, v241
	v_exp_f32_e32 v14, v240
	v_add_f32_e32 v240, v213, v15
	v_max_f32_e32 v241, v47, v47
	v_mov_b32_e32 v143, v213
	v_max_f32_e32 v213, v240, v241
	v_sub_f32_e32 v241, v47, v213
	v_sub_f32_e32 v240, v240, v213
	v_mul_f32_e32 v241, 0x3fb8aa3b, v241
	v_mul_f32_e32 v240, 0x3fb8aa3b, v240
	v_exp_f32_e32 v47, v241
	v_exp_f32_e32 v15, v240
	v_add_f32_e32 v240, v213, v16
	v_max_f32_e32 v241, v48, v48
	v_mov_b32_e32 v144, v213
	v_max_f32_e32 v213, v240, v241
	v_sub_f32_e32 v241, v48, v213
	v_sub_f32_e32 v240, v240, v213
	v_mul_f32_e32 v241, 0x3fb8aa3b, v241
	v_mul_f32_e32 v240, 0x3fb8aa3b, v240
	v_exp_f32_e32 v48, v241
	v_exp_f32_e32 v16, v240
	v_add_f32_e32 v240, v213, v17
	v_max_f32_e32 v241, v49, v49
	v_mov_b32_e32 v145, v213
	v_max_f32_e32 v213, v240, v241
	v_sub_f32_e32 v241, v49, v213
	v_sub_f32_e32 v240, v240, v213
	v_mul_f32_e32 v241, 0x3fb8aa3b, v241
	v_mul_f32_e32 v240, 0x3fb8aa3b, v240
	v_exp_f32_e32 v49, v241
	v_exp_f32_e32 v17, v240
	v_add_f32_e32 v240, v213, v18
	v_max_f32_e32 v241, v50, v50
	v_mov_b32_e32 v146, v213
	v_max_f32_e32 v213, v240, v241
	v_sub_f32_e32 v241, v50, v213
	v_sub_f32_e32 v240, v240, v213
	v_mul_f32_e32 v241, 0x3fb8aa3b, v241
	v_mul_f32_e32 v240, 0x3fb8aa3b, v240
	v_exp_f32_e32 v50, v241
	v_exp_f32_e32 v18, v240
	v_add_f32_e32 v240, v213, v19
	v_max_f32_e32 v241, v51, v51
	v_mov_b32_e32 v147, v213
	v_max_f32_e32 v213, v240, v241
	v_sub_f32_e32 v241, v51, v213
	v_sub_f32_e32 v240, v240, v213
	v_mul_f32_e32 v241, 0x3fb8aa3b, v241
	v_mul_f32_e32 v240, 0x3fb8aa3b, v240
	v_exp_f32_e32 v51, v241
	v_exp_f32_e32 v19, v240
	v_add_f32_e32 v240, v213, v20
	v_max_f32_e32 v241, v52, v52
	v_mov_b32_e32 v148, v213
	v_max_f32_e32 v213, v240, v241
	v_sub_f32_e32 v241, v52, v213
	v_sub_f32_e32 v240, v240, v213
	v_mul_f32_e32 v241, 0x3fb8aa3b, v241
	v_mul_f32_e32 v240, 0x3fb8aa3b, v240
	v_exp_f32_e32 v52, v241
	v_exp_f32_e32 v20, v240
	v_add_f32_e32 v240, v213, v21
	v_max_f32_e32 v241, v53, v53
	v_mov_b32_e32 v149, v213
	v_max_f32_e32 v213, v240, v241
	v_sub_f32_e32 v241, v53, v213
	v_sub_f32_e32 v240, v240, v213
	v_mul_f32_e32 v241, 0x3fb8aa3b, v241
	v_mul_f32_e32 v240, 0x3fb8aa3b, v240
	v_exp_f32_e32 v53, v241
	v_exp_f32_e32 v21, v240
	v_add_f32_e32 v240, v213, v22
	v_max_f32_e32 v241, v54, v54
	v_mov_b32_e32 v150, v213
	v_max_f32_e32 v213, v240, v241
	v_sub_f32_e32 v241, v54, v213
	v_sub_f32_e32 v240, v240, v213
	v_mul_f32_e32 v241, 0x3fb8aa3b, v241
	v_mul_f32_e32 v240, 0x3fb8aa3b, v240
	v_exp_f32_e32 v54, v241
	v_exp_f32_e32 v22, v240
	v_add_f32_e32 v240, v213, v23
	v_max_f32_e32 v241, v55, v55
	v_mov_b32_e32 v151, v213
	v_max_f32_e32 v213, v240, v241
	v_sub_f32_e32 v241, v55, v213
	v_sub_f32_e32 v240, v240, v213
	v_mul_f32_e32 v241, 0x3fb8aa3b, v241
	v_mul_f32_e32 v240, 0x3fb8aa3b, v240
	v_exp_f32_e32 v55, v241
	v_exp_f32_e32 v23, v240
	v_add_f32_e32 v240, v213, v24
	v_max_f32_e32 v241, v56, v56
	v_mov_b32_e32 v152, v213
	v_max_f32_e32 v213, v240, v241
	v_sub_f32_e32 v241, v56, v213
	v_sub_f32_e32 v240, v240, v213
	v_mul_f32_e32 v241, 0x3fb8aa3b, v241
	v_mul_f32_e32 v240, 0x3fb8aa3b, v240
	v_exp_f32_e32 v56, v241
	v_exp_f32_e32 v24, v240
	v_add_f32_e32 v240, v213, v25
	v_max_f32_e32 v241, v57, v57
	v_mov_b32_e32 v153, v213
	v_max_f32_e32 v213, v240, v241
	v_sub_f32_e32 v241, v57, v213
	v_sub_f32_e32 v240, v240, v213
	v_mul_f32_e32 v241, 0x3fb8aa3b, v241
	v_mul_f32_e32 v240, 0x3fb8aa3b, v240
	v_exp_f32_e32 v57, v241
	v_exp_f32_e32 v25, v240
	v_add_f32_e32 v240, v213, v26
	v_max_f32_e32 v241, v58, v58
	v_mov_b32_e32 v154, v213
	v_max_f32_e32 v213, v240, v241
	v_sub_f32_e32 v241, v58, v213
	v_sub_f32_e32 v240, v240, v213
	v_mul_f32_e32 v241, 0x3fb8aa3b, v241
	v_mul_f32_e32 v240, 0x3fb8aa3b, v240
	v_exp_f32_e32 v58, v241
	v_exp_f32_e32 v26, v240
	v_add_f32_e32 v240, v213, v27
	v_max_f32_e32 v241, v59, v59
	v_mov_b32_e32 v155, v213
	v_max_f32_e32 v213, v240, v241
; __device__ __forceinline__ void phase_scan(bf16_t* Cst, float* nst, const float* gch, const float* mloc, float* mprev) {
;     ...
;             for (int c0 = 0; c0 < 32; c0 += 8) {
;                 u32x4 ld[8];
; #pragma unroll
;                 for (int j = 0; j < 8; ++j) ld[j] = *(const u32x4*)(Cst + ((size_t)(bh * 32 + c0 + j) * 65536 + e8 * 8));
; #pragma unroll
;                 for (int j = 0; j < 8; ++j) { const int c = c0 + j; const float gc = gch[bh * 32 + c], mc = mloc[bh * 32 + c];
;                     const float mn = fmaxf(gc + m, mc), aa = __expf(gc + m - mn), bb = __expf(mc - mn);
;                     float lc[8]; unpack8(ld[j], lc);
;                     *(u32x4*)(Cst + ((size_t)(bh * 32 + c) * 65536 + e8 * 8)) = pack8(st);
; #pragma unroll
;                     for (int e = 0; e < 8; ++e) st[e] = aa * st[e] + bb * lc[e];
;                     if (e8 == 0) mprev[bh * 32 + c] = m;
;                     m = mn; }
	v_sub_f32_e32 v241, v59, v213
	v_sub_f32_e32 v240, v240, v213
	v_mul_f32_e32 v241, 0x3fb8aa3b, v241
	v_mul_f32_e32 v240, 0x3fb8aa3b, v240
	v_exp_f32_e32 v59, v241
	v_exp_f32_e32 v27, v240
	v_add_f32_e32 v240, v213, v28
	v_max_f32_e32 v241, v60, v60
	v_mov_b32_e32 v156, v213
	v_max_f32_e32 v213, v240, v241
	v_sub_f32_e32 v241, v60, v213
	v_sub_f32_e32 v240, v240, v213
	v_mul_f32_e32 v241, 0x3fb8aa3b, v241
	v_mul_f32_e32 v240, 0x3fb8aa3b, v240
	v_exp_f32_e32 v60, v241
	v_exp_f32_e32 v28, v240
	v_add_f32_e32 v240, v213, v29
	v_max_f32_e32 v241, v61, v61
	v_mov_b32_e32 v157, v213
	v_max_f32_e32 v213, v240, v241
	v_sub_f32_e32 v241, v61, v213
	v_sub_f32_e32 v240, v240, v213
	v_mul_f32_e32 v241, 0x3fb8aa3b, v241
	v_mul_f32_e32 v240, 0x3fb8aa3b, v240
	v_exp_f32_e32 v61, v241
	v_exp_f32_e32 v29, v240
	v_add_f32_e32 v240, v213, v30
	v_max_f32_e32 v241, v62, v62
	v_mov_b32_e32 v158, v213
	v_max_f32_e32 v213, v240, v241
	v_sub_f32_e32 v241, v62, v213
	v_sub_f32_e32 v240, v240, v213
	v_mul_f32_e32 v241, 0x3fb8aa3b, v241
	v_mul_f32_e32 v240, 0x3fb8aa3b, v240
	v_exp_f32_e32 v62, v241
	v_exp_f32_e32 v30, v240
	v_add_f32_e32 v240, v213, v31
	v_max_f32_e32 v241, v63, v63
	v_mov_b32_e32 v159, v213
	v_max_f32_e32 v213, v240, v241
	v_sub_f32_e32 v241, v63, v213
	v_sub_f32_e32 v240, v240, v213
	v_mul_f32_e32 v241, 0x3fb8aa3b, v241
	v_mul_f32_e32 v240, 0x3fb8aa3b, v240
	v_exp_f32_e32 v63, v241
	v_exp_f32_e32 v31, v240
	v_add_f32_e32 v240, v213, v32
	v_max_f32_e32 v241, v64, v64
	v_mov_b32_e32 v160, v213
	v_max_f32_e32 v213, v240, v241
	v_sub_f32_e32 v241, v64, v213
	v_sub_f32_e32 v240, v240, v213
	v_mul_f32_e32 v241, 0x3fb8aa3b, v241
	v_mul_f32_e32 v240, 0x3fb8aa3b, v240
	v_exp_f32_e32 v64, v241
	v_exp_f32_e32 v32, v240
	v_add_f32_e32 v240, v213, v33
	v_max_f32_e32 v241, v65, v65
	v_mov_b32_e32 v161, v213
	v_max_f32_e32 v213, v240, v241
	v_sub_f32_e32 v241, v65, v213
	v_sub_f32_e32 v240, v240, v213
	v_mul_f32_e32 v241, 0x3fb8aa3b, v241
	v_mul_f32_e32 v240, 0x3fb8aa3b, v240
	v_exp_f32_e32 v65, v241
	v_exp_f32_e32 v33, v240
	s_and_saveexec_b64 s[10:11], s[4:5]
	s_cbranch_execz .Lmy_scan_nomp
	global_store_dword v[238:239], v130, off
	global_store_dword v[238:239], v131, off offset:4
	global_store_dword v[238:239], v132, off offset:8
	global_store_dword v[238:239], v133, off offset:12
	global_store_dword v[238:239], v134, off offset:16
	global_store_dword v[238:239], v135, off offset:20
	global_store_dword v[238:239], v136, off offset:24
	global_store_dword v[238:239], v137, off offset:28
	global_store_dword v[238:239], v138, off offset:32
	global_store_dword v[238:239], v139, off offset:36
	global_store_dword v[238:239], v140, off offset:40
	global_store_dword v[238:239], v141, off offset:44
	global_store_dword v[238:239], v142, off offset:48
	global_store_dword v[238:239], v143, off offset:52
	global_store_dword v[238:239], v144, off offset:56
	global_store_dword v[238:239], v145, off offset:60
	global_store_dword v[238:239], v146, off offset:64
	global_store_dword v[238:239], v147, off offset:68
	global_store_dword v[238:239], v148, off offset:72
	global_store_dword v[238:239], v149, off offset:76
	global_store_dword v[238:239], v150, off offset:80
	global_store_dword v[238:239], v151, off offset:84
	global_store_dword v[238:239], v152, off offset:88
	global_store_dword v[238:239], v153, off offset:92
	global_store_dword v[238:239], v154, off offset:96
	global_store_dword v[238:239], v155, off offset:100
	global_store_dword v[238:239], v156, off offset:104
	global_store_dword v[238:239], v157, off offset:108
	global_store_dword v[238:239], v158, off offset:112
	global_store_dword v[238:239], v159, off offset:116
	global_store_dword v[238:239], v160, off offset:120
	global_store_dword v[238:239], v161, off offset:124
.Lmy_scan_nomp:
	s_or_b64 exec, exec, s[10:11]
	s_nop 1
	global_load_dwordx4 v[130:133], v[214:215], off
	v_lshl_add_u64 v[214:215], v[214:215], 0, s[100:101]
	global_load_dwordx4 v[134:137], v[214:215], off
	v_lshl_add_u64 v[214:215], v[214:215], 0, s[100:101]
	global_load_dwordx4 v[138:141], v[214:215], off
	v_lshl_add_u64 v[214:215], v[214:215], 0, s[100:101]
	global_load_dwordx4 v[142:145], v[214:215], off
	v_lshl_add_u64 v[214:215], v[214:215], 0, s[100:101]
	global_load_dwordx4 v[146:149], v[214:215], off
	v_lshl_add_u64 v[214:215], v[214:215], 0, s[100:101]
	global_load_dwordx4 v[150:153], v[214:215], off
	v_lshl_add_u64 v[214:215], v[214:215], 0, s[100:101]
	global_load_dwordx4 v[154:157], v[214:215], off
	v_lshl_add_u64 v[214:215], v[214:215], 0, s[100:101]
	global_load_dwordx4 v[158:161], v[214:215], off
	v_lshl_add_u64 v[214:215], v[214:215], 0, s[100:101]
	global_load_dwordx4 v[162:165], v[214:215], off
	v_lshl_add_u64 v[214:215], v[214:215], 0, s[100:101]
	global_load_dwordx4 v[166:169], v[214:215], off
	v_lshl_add_u64 v[214:215], v[214:215], 0, s[100:101]
	global_load_dwordx4 v[170:173], v[214:215], off
	v_lshl_add_u64 v[214:215], v[214:215], 0, s[100:101]
	global_load_dwordx4 v[174:177], v[214:215], off
	v_lshl_add_u64 v[214:215], v[214:215], 0, s[100:101]
	global_load_dwordx4 v[178:181], v[214:215], off
	v_lshl_add_u64 v[214:215], v[214:215], 0, s[100:101]
	global_load_dwordx4 v[182:185], v[214:215], off
	v_lshl_add_u64 v[214:215], v[214:215], 0, s[100:101]
	global_load_dwordx4 v[186:189], v[214:215], off
	v_lshl_add_u64 v[214:215], v[214:215], 0, s[100:101]
	global_load_dwordx4 v[190:193], v[214:215], off
	s_waitcnt vmcnt(31)
; __device__ __forceinline__ void phase_scan(bf16_t* Cst, float* nst, const float* gch, const float* mloc, float* mprev) {
;     ...
;                 for (int j = 0; j < 8; ++j) ld[j] = *(const u32x4*)(Cst + ((size_t)(bh * 32 + c0 + j) * 65536 + e8 * 8));
; #pragma unroll
;                 for (int j = 0; j < 8; ++j) { const int c = c0 + j; const float gc = gch[bh * 32 + c], mc = mloc[bh * 32 + c];
;                     const float mn = fmaxf(gc + m, mc), aa = __expf(gc + m - mn), bb = __expf(mc - mn);
;                     float lc[8]; unpack8(ld[j], lc);
;                     *(u32x4*)(Cst + ((size_t)(bh * 32 + c) * 65536 + e8 * 8)) = pack8(st);
; #pragma unroll
;                     for (int e = 0; e < 8; ++e) st[e] = aa * st[e] + bb * lc[e];
	v_cvt_pk_bf16_f32 v220, v205, v206
	v_cvt_pk_bf16_f32 v221, v207, v208
	v_cvt_pk_bf16_f32 v222, v209, v210
	v_cvt_pk_bf16_f32 v223, v211, v212
	global_store_dwordx4 v[216:217], v[220:223], off
	v_lshl_add_u64 v[216:217], v[216:217], 0, s[100:101]
	v_lshlrev_b32_e32 v224, 16, v66
	v_and_b32_e32 v225, 0xffff0000, v66
	v_lshlrev_b32_e32 v226, 16, v67
	v_and_b32_e32 v227, 0xffff0000, v67
	v_lshlrev_b32_e32 v228, 16, v68
	v_and_b32_e32 v229, 0xffff0000, v68
	v_lshlrev_b32_e32 v230, 16, v69
	v_and_b32_e32 v231, 0xffff0000, v69
	v_mul_f32_e32 v224, v34, v224
	v_mul_f32_e32 v225, v34, v225
	v_mul_f32_e32 v226, v34, v226
	v_mul_f32_e32 v227, v34, v227
	v_mul_f32_e32 v228, v34, v228
	v_mul_f32_e32 v229, v34, v229
	v_mul_f32_e32 v230, v34, v230
	v_mul_f32_e32 v231, v34, v231
	v_fma_f32 v205, v205, v2, v224
	v_fma_f32 v206, v206, v2, v225
	v_fma_f32 v207, v207, v2, v226
	v_fma_f32 v208, v208, v2, v227
	v_fma_f32 v209, v209, v2, v228
	v_fma_f32 v210, v210, v2, v229
	v_fma_f32 v211, v211, v2, v230
	v_fma_f32 v212, v212, v2, v231
	s_waitcnt vmcnt(31)
	v_cvt_pk_bf16_f32 v220, v205, v206
	v_cvt_pk_bf16_f32 v221, v207, v208
	v_cvt_pk_bf16_f32 v222, v209, v210
	v_cvt_pk_bf16_f32 v223, v211, v212
	global_store_dwordx4 v[216:217], v[220:223], off
	v_lshl_add_u64 v[216:217], v[216:217], 0, s[100:101]
	v_lshlrev_b32_e32 v224, 16, v70
	v_and_b32_e32 v225, 0xffff0000, v70
	v_lshlrev_b32_e32 v226, 16, v71
	v_and_b32_e32 v227, 0xffff0000, v71
	v_lshlrev_b32_e32 v228, 16, v72
	v_and_b32_e32 v229, 0xffff0000, v72
	v_lshlrev_b32_e32 v230, 16, v73
	v_and_b32_e32 v231, 0xffff0000, v73
	v_mul_f32_e32 v224, v35, v224
	v_mul_f32_e32 v225, v35, v225
	v_mul_f32_e32 v226, v35, v226
	v_mul_f32_e32 v227, v35, v227
	v_mul_f32_e32 v228, v35, v228
	v_mul_f32_e32 v229, v35, v229
	v_mul_f32_e32 v230, v35, v230
	v_mul_f32_e32 v231, v35, v231
	v_fma_f32 v205, v205, v3, v224
	v_fma_f32 v206, v206, v3, v225
	v_fma_f32 v207, v207, v3, v226
	v_fma_f32 v208, v208, v3, v227
	v_fma_f32 v209, v209, v3, v228
	v_fma_f32 v210, v210, v3, v229
	v_fma_f32 v211, v211, v3, v230
	v_fma_f32 v212, v212, v3, v231
	s_waitcnt vmcnt(31)
	v_cvt_pk_bf16_f32 v220, v205, v206
	v_cvt_pk_bf16_f32 v221, v207, v208
	v_cvt_pk_bf16_f32 v222, v209, v210
	v_cvt_pk_bf16_f32 v223, v211, v212
	global_store_dwordx4 v[216:217], v[220:223], off
	v_lshl_add_u64 v[216:217], v[216:217], 0, s[100:101]
	v_lshlrev_b32_e32 v224, 16, v74
	v_and_b32_e32 v225, 0xffff0000, v74
	v_lshlrev_b32_e32 v226, 16, v75
	v_and_b32_e32 v227, 0xffff0000, v75
	v_lshlrev_b32_e32 v228, 16, v76
	v_and_b32_e32 v229, 0xffff0000, v76
	v_lshlrev_b32_e32 v230, 16, v77
	v_and_b32_e32 v231, 0xffff0000, v77
	v_mul_f32_e32 v224, v36, v224
	v_mul_f32_e32 v225, v36, v225
	v_mul_f32_e32 v226, v36, v226
	v_mul_f32_e32 v227, v36, v227
	v_mul_f32_e32 v228, v36, v228
	v_mul_f32_e32 v229, v36, v229
	v_mul_f32_e32 v230, v36, v230
	v_mul_f32_e32 v231, v36, v231
	v_fma_f32 v205, v205, v4, v224
	v_fma_f32 v206, v206, v4, v225
	v_fma_f32 v207, v207, v4, v226
	v_fma_f32 v208, v208, v4, v227
	v_fma_f32 v209, v209, v4, v228
	v_fma_f32 v210, v210, v4, v229
	v_fma_f32 v211, v211, v4, v230
	v_fma_f32 v212, v212, v4, v231
	s_waitcnt vmcnt(31)
	v_cvt_pk_bf16_f32 v220, v205, v206
	v_cvt_pk_bf16_f32 v221, v207, v208
	v_cvt_pk_bf16_f32 v222, v209, v210
	v_cvt_pk_bf16_f32 v223, v211, v212
	global_store_dwordx4 v[216:217], v[220:223], off
	v_lshl_add_u64 v[216:217], v[216:217], 0, s[100:101]
	v_lshlrev_b32_e32 v224, 16, v78
	v_and_b32_e32 v225, 0xffff0000, v78
	v_lshlrev_b32_e32 v226, 16, v79
	v_and_b32_e32 v227, 0xffff0000, v79
	v_lshlrev_b32_e32 v228, 16, v80
	v_and_b32_e32 v229, 0xffff0000, v80
	v_lshlrev_b32_e32 v230, 16, v81
	v_and_b32_e32 v231, 0xffff0000, v81
	v_mul_f32_e32 v224, v37, v224
	v_mul_f32_e32 v225, v37, v225
	v_mul_f32_e32 v226, v37, v226
	v_mul_f32_e32 v227, v37, v227
	v_mul_f32_e32 v228, v37, v228
	v_mul_f32_e32 v229, v37, v229
	v_mul_f32_e32 v230, v37, v230
	v_mul_f32_e32 v231, v37, v231
	v_fma_f32 v205, v205, v5, v224
	v_fma_f32 v206, v206, v5, v225
	v_fma_f32 v207, v207, v5, v226
	v_fma_f32 v208, v208, v5, v227
	v_fma_f32 v209, v209, v5, v228
	v_fma_f32 v210, v210, v5, v229
	v_fma_f32 v211, v211, v5, v230
	v_fma_f32 v212, v212, v5, v231
	s_waitcnt vmcnt(31)
	v_cvt_pk_bf16_f32 v220, v205, v206
	v_cvt_pk_bf16_f32 v221, v207, v208
	v_cvt_pk_bf16_f32 v222, v209, v210
	v_cvt_pk_bf16_f32 v223, v211, v212
	global_store_dwordx4 v[216:217], v[220:223], off
	v_lshl_add_u64 v[216:217], v[216:217], 0, s[100:101]
	v_lshlrev_b32_e32 v224, 16, v82
	v_and_b32_e32 v225, 0xffff0000, v82
	v_lshlrev_b32_e32 v226, 16, v83
	v_and_b32_e32 v227, 0xffff0000, v83
	v_lshlrev_b32_e32 v228, 16, v84
	v_and_b32_e32 v229, 0xffff0000, v84
	v_lshlrev_b32_e32 v230, 16, v85
	v_and_b32_e32 v231, 0xffff0000, v85
	v_mul_f32_e32 v224, v38, v224
	v_mul_f32_e32 v225, v38, v225
	v_mul_f32_e32 v226, v38, v226
	v_mul_f32_e32 v227, v38, v227
	v_mul_f32_e32 v228, v38, v228
	v_mul_f32_e32 v229, v38, v229
	v_mul_f32_e32 v230, v38, v230
	v_mul_f32_e32 v231, v38, v231
	v_fma_f32 v205, v205, v6, v224
	v_fma_f32 v206, v206, v6, v225
	v_fma_f32 v207, v207, v6, v226
	v_fma_f32 v208, v208, v6, v227
	v_fma_f32 v209, v209, v6, v228
	v_fma_f32 v210, v210, v6, v229
	v_fma_f32 v211, v211, v6, v230
	v_fma_f32 v212, v212, v6, v231
	s_waitcnt vmcnt(31)
; __device__ __forceinline__ void phase_scan(bf16_t* Cst, float* nst, const float* gch, const float* mloc, float* mprev) {
;     ...
;                 for (int j = 0; j < 8; ++j) ld[j] = *(const u32x4*)(Cst + ((size_t)(bh * 32 + c0 + j) * 65536 + e8 * 8));
; #pragma unroll
;                 for (int j = 0; j < 8; ++j) { const int c = c0 + j; const float gc = gch[bh * 32 + c], mc = mloc[bh * 32 + c];
;                     const float mn = fmaxf(gc + m, mc), aa = __expf(gc + m - mn), bb = __expf(mc - mn);
;                     float lc[8]; unpack8(ld[j], lc);
;                     *(u32x4*)(Cst + ((size_t)(bh * 32 + c) * 65536 + e8 * 8)) = pack8(st);
; #pragma unroll
;                     for (int e = 0; e < 8; ++e) st[e] = aa * st[e] + bb * lc[e];
	v_cvt_pk_bf16_f32 v220, v205, v206
	v_cvt_pk_bf16_f32 v221, v207, v208
	v_cvt_pk_bf16_f32 v222, v209, v210
	v_cvt_pk_bf16_f32 v223, v211, v212
	global_store_dwordx4 v[216:217], v[220:223], off
	v_lshl_add_u64 v[216:217], v[216:217], 0, s[100:101]
	v_lshlrev_b32_e32 v224, 16, v86
	v_and_b32_e32 v225, 0xffff0000, v86
	v_lshlrev_b32_e32 v226, 16, v87
	v_and_b32_e32 v227, 0xffff0000, v87
	v_lshlrev_b32_e32 v228, 16, v88
	v_and_b32_e32 v229, 0xffff0000, v88
	v_lshlrev_b32_e32 v230, 16, v89
	v_and_b32_e32 v231, 0xffff0000, v89
	v_mul_f32_e32 v224, v39, v224
	v_mul_f32_e32 v225, v39, v225
	v_mul_f32_e32 v226, v39, v226
	v_mul_f32_e32 v227, v39, v227
	v_mul_f32_e32 v228, v39, v228
	v_mul_f32_e32 v229, v39, v229
	v_mul_f32_e32 v230, v39, v230
	v_mul_f32_e32 v231, v39, v231
	v_fma_f32 v205, v205, v7, v224
	v_fma_f32 v206, v206, v7, v225
	v_fma_f32 v207, v207, v7, v226
	v_fma_f32 v208, v208, v7, v227
	v_fma_f32 v209, v209, v7, v228
	v_fma_f32 v210, v210, v7, v229
	v_fma_f32 v211, v211, v7, v230
	v_fma_f32 v212, v212, v7, v231
	s_waitcnt vmcnt(31)
	v_cvt_pk_bf16_f32 v220, v205, v206
	v_cvt_pk_bf16_f32 v221, v207, v208
	v_cvt_pk_bf16_f32 v222, v209, v210
	v_cvt_pk_bf16_f32 v223, v211, v212
	global_store_dwordx4 v[216:217], v[220:223], off
	v_lshl_add_u64 v[216:217], v[216:217], 0, s[100:101]
	v_lshlrev_b32_e32 v224, 16, v90
	v_and_b32_e32 v225, 0xffff0000, v90
	v_lshlrev_b32_e32 v226, 16, v91
	v_and_b32_e32 v227, 0xffff0000, v91
	v_lshlrev_b32_e32 v228, 16, v92
	v_and_b32_e32 v229, 0xffff0000, v92
	v_lshlrev_b32_e32 v230, 16, v93
	v_and_b32_e32 v231, 0xffff0000, v93
	v_mul_f32_e32 v224, v40, v224
	v_mul_f32_e32 v225, v40, v225
	v_mul_f32_e32 v226, v40, v226
	v_mul_f32_e32 v227, v40, v227
	v_mul_f32_e32 v228, v40, v228
	v_mul_f32_e32 v229, v40, v229
	v_mul_f32_e32 v230, v40, v230
	v_mul_f32_e32 v231, v40, v231
	v_fma_f32 v205, v205, v8, v224
	v_fma_f32 v206, v206, v8, v225
	v_fma_f32 v207, v207, v8, v226
	v_fma_f32 v208, v208, v8, v227
	v_fma_f32 v209, v209, v8, v228
	v_fma_f32 v210, v210, v8, v229
	v_fma_f32 v211, v211, v8, v230
	v_fma_f32 v212, v212, v8, v231
	s_waitcnt vmcnt(31)
	v_cvt_pk_bf16_f32 v220, v205, v206
	v_cvt_pk_bf16_f32 v221, v207, v208
	v_cvt_pk_bf16_f32 v222, v209, v210
	v_cvt_pk_bf16_f32 v223, v211, v212
	global_store_dwordx4 v[216:217], v[220:223], off
	v_lshl_add_u64 v[216:217], v[216:217], 0, s[100:101]
	v_lshlrev_b32_e32 v224, 16, v94
	v_and_b32_e32 v225, 0xffff0000, v94
	v_lshlrev_b32_e32 v226, 16, v95
	v_and_b32_e32 v227, 0xffff0000, v95
	v_lshlrev_b32_e32 v228, 16, v96
	v_and_b32_e32 v229, 0xffff0000, v96
	v_lshlrev_b32_e32 v230, 16, v97
	v_and_b32_e32 v231, 0xffff0000, v97
	v_mul_f32_e32 v224, v41, v224
	v_mul_f32_e32 v225, v41, v225
	v_mul_f32_e32 v226, v41, v226
	v_mul_f32_e32 v227, v41, v227
	v_mul_f32_e32 v228, v41, v228
	v_mul_f32_e32 v229, v41, v229
	v_mul_f32_e32 v230, v41, v230
	v_mul_f32_e32 v231, v41, v231
	v_fma_f32 v205, v205, v9, v224
	v_fma_f32 v206, v206, v9, v225
	v_fma_f32 v207, v207, v9, v226
	v_fma_f32 v208, v208, v9, v227
	v_fma_f32 v209, v209, v9, v228
	v_fma_f32 v210, v210, v9, v229
	v_fma_f32 v211, v211, v9, v230
	v_fma_f32 v212, v212, v9, v231
	s_waitcnt vmcnt(31)
	v_cvt_pk_bf16_f32 v220, v205, v206
	v_cvt_pk_bf16_f32 v221, v207, v208
	v_cvt_pk_bf16_f32 v222, v209, v210
	v_cvt_pk_bf16_f32 v223, v211, v212
	global_store_dwordx4 v[216:217], v[220:223], off
	v_lshl_add_u64 v[216:217], v[216:217], 0, s[100:101]
	v_lshlrev_b32_e32 v224, 16, v98
	v_and_b32_e32 v225, 0xffff0000, v98
	v_lshlrev_b32_e32 v226, 16, v99
	v_and_b32_e32 v227, 0xffff0000, v99
	v_lshlrev_b32_e32 v228, 16, v100
	v_and_b32_e32 v229, 0xffff0000, v100
	v_lshlrev_b32_e32 v230, 16, v101
	v_and_b32_e32 v231, 0xffff0000, v101
	v_mul_f32_e32 v224, v42, v224
	v_mul_f32_e32 v225, v42, v225
	v_mul_f32_e32 v226, v42, v226
	v_mul_f32_e32 v227, v42, v227
	v_mul_f32_e32 v228, v42, v228
	v_mul_f32_e32 v229, v42, v229
	v_mul_f32_e32 v230, v42, v230
	v_mul_f32_e32 v231, v42, v231
	v_fma_f32 v205, v205, v10, v224
	v_fma_f32 v206, v206, v10, v225
	v_fma_f32 v207, v207, v10, v226
	v_fma_f32 v208, v208, v10, v227
	v_fma_f32 v209, v209, v10, v228
	v_fma_f32 v210, v210, v10, v229
	v_fma_f32 v211, v211, v10, v230
	v_fma_f32 v212, v212, v10, v231
	s_waitcnt vmcnt(31)
	v_cvt_pk_bf16_f32 v220, v205, v206
	v_cvt_pk_bf16_f32 v221, v207, v208
	v_cvt_pk_bf16_f32 v222, v209, v210
	v_cvt_pk_bf16_f32 v223, v211, v212
	global_store_dwordx4 v[216:217], v[220:223], off
	v_lshl_add_u64 v[216:217], v[216:217], 0, s[100:101]
	v_lshlrev_b32_e32 v224, 16, v102
	v_and_b32_e32 v225, 0xffff0000, v102
	v_lshlrev_b32_e32 v226, 16, v103
	v_and_b32_e32 v227, 0xffff0000, v103
	v_lshlrev_b32_e32 v228, 16, v104
	v_and_b32_e32 v229, 0xffff0000, v104
	v_lshlrev_b32_e32 v230, 16, v105
	v_and_b32_e32 v231, 0xffff0000, v105
	v_mul_f32_e32 v224, v43, v224
	v_mul_f32_e32 v225, v43, v225
	v_mul_f32_e32 v226, v43, v226
	v_mul_f32_e32 v227, v43, v227
	v_mul_f32_e32 v228, v43, v228
	v_mul_f32_e32 v229, v43, v229
	v_mul_f32_e32 v230, v43, v230
	v_mul_f32_e32 v231, v43, v231
	v_fma_f32 v205, v205, v11, v224
	v_fma_f32 v206, v206, v11, v225
	v_fma_f32 v207, v207, v11, v226
	v_fma_f32 v208, v208, v11, v227
	v_fma_f32 v209, v209, v11, v228
	v_fma_f32 v210, v210, v11, v229
	v_fma_f32 v211, v211, v11, v230
	v_fma_f32 v212, v212, v11, v231
	s_waitcnt vmcnt(31)
; __device__ __forceinline__ void phase_scan(bf16_t* Cst, float* nst, const float* gch, const float* mloc, float* mprev) {
;     ...
;                 for (int j = 0; j < 8; ++j) ld[j] = *(const u32x4*)(Cst + ((size_t)(bh * 32 + c0 + j) * 65536 + e8 * 8));
; #pragma unroll
;                 for (int j = 0; j < 8; ++j) { const int c = c0 + j; const float gc = gch[bh * 32 + c], mc = mloc[bh * 32 + c];
;                     const float mn = fmaxf(gc + m, mc), aa = __expf(gc + m - mn), bb = __expf(mc - mn);
;                     float lc[8]; unpack8(ld[j], lc);
;                     *(u32x4*)(Cst + ((size_t)(bh * 32 + c) * 65536 + e8 * 8)) = pack8(st);
; #pragma unroll
;                     for (int e = 0; e < 8; ++e) st[e] = aa * st[e] + bb * lc[e];
	v_cvt_pk_bf16_f32 v220, v205, v206
	v_cvt_pk_bf16_f32 v221, v207, v208
	v_cvt_pk_bf16_f32 v222, v209, v210
	v_cvt_pk_bf16_f32 v223, v211, v212
	global_store_dwordx4 v[216:217], v[220:223], off
	v_lshl_add_u64 v[216:217], v[216:217], 0, s[100:101]
	v_lshlrev_b32_e32 v224, 16, v106
	v_and_b32_e32 v225, 0xffff0000, v106
	v_lshlrev_b32_e32 v226, 16, v107
	v_and_b32_e32 v227, 0xffff0000, v107
	v_lshlrev_b32_e32 v228, 16, v108
	v_and_b32_e32 v229, 0xffff0000, v108
	v_lshlrev_b32_e32 v230, 16, v109
	v_and_b32_e32 v231, 0xffff0000, v109
	v_mul_f32_e32 v224, v44, v224
	v_mul_f32_e32 v225, v44, v225
	v_mul_f32_e32 v226, v44, v226
	v_mul_f32_e32 v227, v44, v227
	v_mul_f32_e32 v228, v44, v228
	v_mul_f32_e32 v229, v44, v229
	v_mul_f32_e32 v230, v44, v230
	v_mul_f32_e32 v231, v44, v231
	v_fma_f32 v205, v205, v12, v224
	v_fma_f32 v206, v206, v12, v225
	v_fma_f32 v207, v207, v12, v226
	v_fma_f32 v208, v208, v12, v227
	v_fma_f32 v209, v209, v12, v228
	v_fma_f32 v210, v210, v12, v229
	v_fma_f32 v211, v211, v12, v230
	v_fma_f32 v212, v212, v12, v231
	s_waitcnt vmcnt(31)
	v_cvt_pk_bf16_f32 v220, v205, v206
	v_cvt_pk_bf16_f32 v221, v207, v208
	v_cvt_pk_bf16_f32 v222, v209, v210
	v_cvt_pk_bf16_f32 v223, v211, v212
	global_store_dwordx4 v[216:217], v[220:223], off
	v_lshl_add_u64 v[216:217], v[216:217], 0, s[100:101]
	v_lshlrev_b32_e32 v224, 16, v110
	v_and_b32_e32 v225, 0xffff0000, v110
	v_lshlrev_b32_e32 v226, 16, v111
	v_and_b32_e32 v227, 0xffff0000, v111
	v_lshlrev_b32_e32 v228, 16, v112
	v_and_b32_e32 v229, 0xffff0000, v112
	v_lshlrev_b32_e32 v230, 16, v113
	v_and_b32_e32 v231, 0xffff0000, v113
	v_mul_f32_e32 v224, v45, v224
	v_mul_f32_e32 v225, v45, v225
	v_mul_f32_e32 v226, v45, v226
	v_mul_f32_e32 v227, v45, v227
	v_mul_f32_e32 v228, v45, v228
	v_mul_f32_e32 v229, v45, v229
	v_mul_f32_e32 v230, v45, v230
	v_mul_f32_e32 v231, v45, v231
	v_fma_f32 v205, v205, v13, v224
	v_fma_f32 v206, v206, v13, v225
	v_fma_f32 v207, v207, v13, v226
	v_fma_f32 v208, v208, v13, v227
	v_fma_f32 v209, v209, v13, v228
	v_fma_f32 v210, v210, v13, v229
	v_fma_f32 v211, v211, v13, v230
	v_fma_f32 v212, v212, v13, v231
	s_waitcnt vmcnt(31)
	v_cvt_pk_bf16_f32 v220, v205, v206
	v_cvt_pk_bf16_f32 v221, v207, v208
	v_cvt_pk_bf16_f32 v222, v209, v210
	v_cvt_pk_bf16_f32 v223, v211, v212
	global_store_dwordx4 v[216:217], v[220:223], off
	v_lshl_add_u64 v[216:217], v[216:217], 0, s[100:101]
	v_lshlrev_b32_e32 v224, 16, v114
	v_and_b32_e32 v225, 0xffff0000, v114
	v_lshlrev_b32_e32 v226, 16, v115
	v_and_b32_e32 v227, 0xffff0000, v115
	v_lshlrev_b32_e32 v228, 16, v116
	v_and_b32_e32 v229, 0xffff0000, v116
	v_lshlrev_b32_e32 v230, 16, v117
	v_and_b32_e32 v231, 0xffff0000, v117
	v_mul_f32_e32 v224, v46, v224
	v_mul_f32_e32 v225, v46, v225
	v_mul_f32_e32 v226, v46, v226
	v_mul_f32_e32 v227, v46, v227
	v_mul_f32_e32 v228, v46, v228
	v_mul_f32_e32 v229, v46, v229
	v_mul_f32_e32 v230, v46, v230
	v_mul_f32_e32 v231, v46, v231
	v_fma_f32 v205, v205, v14, v224
	v_fma_f32 v206, v206, v14, v225
	v_fma_f32 v207, v207, v14, v226
	v_fma_f32 v208, v208, v14, v227
	v_fma_f32 v209, v209, v14, v228
	v_fma_f32 v210, v210, v14, v229
	v_fma_f32 v211, v211, v14, v230
	v_fma_f32 v212, v212, v14, v231
	s_waitcnt vmcnt(31)
	v_cvt_pk_bf16_f32 v220, v205, v206
	v_cvt_pk_bf16_f32 v221, v207, v208
	v_cvt_pk_bf16_f32 v222, v209, v210
	v_cvt_pk_bf16_f32 v223, v211, v212
	global_store_dwordx4 v[216:217], v[220:223], off
	v_lshl_add_u64 v[216:217], v[216:217], 0, s[100:101]
	v_lshlrev_b32_e32 v224, 16, v118
	v_and_b32_e32 v225, 0xffff0000, v118
	v_lshlrev_b32_e32 v226, 16, v119
	v_and_b32_e32 v227, 0xffff0000, v119
	v_lshlrev_b32_e32 v228, 16, v120
	v_and_b32_e32 v229, 0xffff0000, v120
	v_lshlrev_b32_e32 v230, 16, v121
	v_and_b32_e32 v231, 0xffff0000, v121
	v_mul_f32_e32 v224, v47, v224
	v_mul_f32_e32 v225, v47, v225
	v_mul_f32_e32 v226, v47, v226
	v_mul_f32_e32 v227, v47, v227
	v_mul_f32_e32 v228, v47, v228
	v_mul_f32_e32 v229, v47, v229
	v_mul_f32_e32 v230, v47, v230
	v_mul_f32_e32 v231, v47, v231
	v_fma_f32 v205, v205, v15, v224
	v_fma_f32 v206, v206, v15, v225
	v_fma_f32 v207, v207, v15, v226
	v_fma_f32 v208, v208, v15, v227
	v_fma_f32 v209, v209, v15, v228
	v_fma_f32 v210, v210, v15, v229
	v_fma_f32 v211, v211, v15, v230
	v_fma_f32 v212, v212, v15, v231
	s_waitcnt vmcnt(31)
	v_cvt_pk_bf16_f32 v220, v205, v206
	v_cvt_pk_bf16_f32 v221, v207, v208
	v_cvt_pk_bf16_f32 v222, v209, v210
	v_cvt_pk_bf16_f32 v223, v211, v212
	global_store_dwordx4 v[216:217], v[220:223], off
	v_lshl_add_u64 v[216:217], v[216:217], 0, s[100:101]
	v_lshlrev_b32_e32 v224, 16, v122
	v_and_b32_e32 v225, 0xffff0000, v122
	v_lshlrev_b32_e32 v226, 16, v123
	v_and_b32_e32 v227, 0xffff0000, v123
	v_lshlrev_b32_e32 v228, 16, v124
	v_and_b32_e32 v229, 0xffff0000, v124
	v_lshlrev_b32_e32 v230, 16, v125
	v_and_b32_e32 v231, 0xffff0000, v125
	v_mul_f32_e32 v224, v48, v224
	v_mul_f32_e32 v225, v48, v225
	v_mul_f32_e32 v226, v48, v226
	v_mul_f32_e32 v227, v48, v227
	v_mul_f32_e32 v228, v48, v228
	v_mul_f32_e32 v229, v48, v229
	v_mul_f32_e32 v230, v48, v230
	v_mul_f32_e32 v231, v48, v231
	v_fma_f32 v205, v205, v16, v224
	v_fma_f32 v206, v206, v16, v225
	v_fma_f32 v207, v207, v16, v226
	v_fma_f32 v208, v208, v16, v227
	v_fma_f32 v209, v209, v16, v228
	v_fma_f32 v210, v210, v16, v229
	v_fma_f32 v211, v211, v16, v230
	v_fma_f32 v212, v212, v16, v231
	s_waitcnt vmcnt(31)
; __device__ __forceinline__ void phase_scan(bf16_t* Cst, float* nst, const float* gch, const float* mloc, float* mprev) {
;     ...
;                 for (int j = 0; j < 8; ++j) ld[j] = *(const u32x4*)(Cst + ((size_t)(bh * 32 + c0 + j) * 65536 + e8 * 8));
; #pragma unroll
;                 for (int j = 0; j < 8; ++j) { const int c = c0 + j; const float gc = gch[bh * 32 + c], mc = mloc[bh * 32 + c];
;                     const float mn = fmaxf(gc + m, mc), aa = __expf(gc + m - mn), bb = __expf(mc - mn);
;                     float lc[8]; unpack8(ld[j], lc);
;                     *(u32x4*)(Cst + ((size_t)(bh * 32 + c) * 65536 + e8 * 8)) = pack8(st);
; #pragma unroll
;                     for (int e = 0; e < 8; ++e) st[e] = aa * st[e] + bb * lc[e];
	v_cvt_pk_bf16_f32 v220, v205, v206
	v_cvt_pk_bf16_f32 v221, v207, v208
	v_cvt_pk_bf16_f32 v222, v209, v210
	v_cvt_pk_bf16_f32 v223, v211, v212
	global_store_dwordx4 v[216:217], v[220:223], off
	v_lshl_add_u64 v[216:217], v[216:217], 0, s[100:101]
	v_lshlrev_b32_e32 v224, 16, v126
	v_and_b32_e32 v225, 0xffff0000, v126
	v_lshlrev_b32_e32 v226, 16, v127
	v_and_b32_e32 v227, 0xffff0000, v127
	v_lshlrev_b32_e32 v228, 16, v128
	v_and_b32_e32 v229, 0xffff0000, v128
	v_lshlrev_b32_e32 v230, 16, v129
	v_and_b32_e32 v231, 0xffff0000, v129
	v_mul_f32_e32 v224, v49, v224
	v_mul_f32_e32 v225, v49, v225
	v_mul_f32_e32 v226, v49, v226
	v_mul_f32_e32 v227, v49, v227
	v_mul_f32_e32 v228, v49, v228
	v_mul_f32_e32 v229, v49, v229
	v_mul_f32_e32 v230, v49, v230
	v_mul_f32_e32 v231, v49, v231
	v_fma_f32 v205, v205, v17, v224
	v_fma_f32 v206, v206, v17, v225
	v_fma_f32 v207, v207, v17, v226
	v_fma_f32 v208, v208, v17, v227
	v_fma_f32 v209, v209, v17, v228
	v_fma_f32 v210, v210, v17, v229
	v_fma_f32 v211, v211, v17, v230
	v_fma_f32 v212, v212, v17, v231
	s_waitcnt vmcnt(31)
	v_cvt_pk_bf16_f32 v220, v205, v206
	v_cvt_pk_bf16_f32 v221, v207, v208
	v_cvt_pk_bf16_f32 v222, v209, v210
	v_cvt_pk_bf16_f32 v223, v211, v212
	global_store_dwordx4 v[216:217], v[220:223], off
	v_lshl_add_u64 v[216:217], v[216:217], 0, s[100:101]
	v_lshlrev_b32_e32 v224, 16, v130
	v_and_b32_e32 v225, 0xffff0000, v130
	v_lshlrev_b32_e32 v226, 16, v131
	v_and_b32_e32 v227, 0xffff0000, v131
	v_lshlrev_b32_e32 v228, 16, v132
	v_and_b32_e32 v229, 0xffff0000, v132
	v_lshlrev_b32_e32 v230, 16, v133
	v_and_b32_e32 v231, 0xffff0000, v133
	v_mul_f32_e32 v224, v50, v224
	v_mul_f32_e32 v225, v50, v225
	v_mul_f32_e32 v226, v50, v226
	v_mul_f32_e32 v227, v50, v227
	v_mul_f32_e32 v228, v50, v228
	v_mul_f32_e32 v229, v50, v229
	v_mul_f32_e32 v230, v50, v230
	v_mul_f32_e32 v231, v50, v231
	v_fma_f32 v205, v205, v18, v224
	v_fma_f32 v206, v206, v18, v225
	v_fma_f32 v207, v207, v18, v226
	v_fma_f32 v208, v208, v18, v227
	v_fma_f32 v209, v209, v18, v228
	v_fma_f32 v210, v210, v18, v229
	v_fma_f32 v211, v211, v18, v230
	v_fma_f32 v212, v212, v18, v231
	s_waitcnt vmcnt(31)
	v_cvt_pk_bf16_f32 v220, v205, v206
	v_cvt_pk_bf16_f32 v221, v207, v208
	v_cvt_pk_bf16_f32 v222, v209, v210
	v_cvt_pk_bf16_f32 v223, v211, v212
	global_store_dwordx4 v[216:217], v[220:223], off
	v_lshl_add_u64 v[216:217], v[216:217], 0, s[100:101]
	v_lshlrev_b32_e32 v224, 16, v134
	v_and_b32_e32 v225, 0xffff0000, v134
	v_lshlrev_b32_e32 v226, 16, v135
	v_and_b32_e32 v227, 0xffff0000, v135
	v_lshlrev_b32_e32 v228, 16, v136
	v_and_b32_e32 v229, 0xffff0000, v136
	v_lshlrev_b32_e32 v230, 16, v137
	v_and_b32_e32 v231, 0xffff0000, v137
	v_mul_f32_e32 v224, v51, v224
	v_mul_f32_e32 v225, v51, v225
	v_mul_f32_e32 v226, v51, v226
	v_mul_f32_e32 v227, v51, v227
	v_mul_f32_e32 v228, v51, v228
	v_mul_f32_e32 v229, v51, v229
	v_mul_f32_e32 v230, v51, v230
	v_mul_f32_e32 v231, v51, v231
	v_fma_f32 v205, v205, v19, v224
	v_fma_f32 v206, v206, v19, v225
	v_fma_f32 v207, v207, v19, v226
	v_fma_f32 v208, v208, v19, v227
	v_fma_f32 v209, v209, v19, v228
	v_fma_f32 v210, v210, v19, v229
	v_fma_f32 v211, v211, v19, v230
	v_fma_f32 v212, v212, v19, v231
	s_waitcnt vmcnt(31)
	v_cvt_pk_bf16_f32 v220, v205, v206
	v_cvt_pk_bf16_f32 v221, v207, v208
	v_cvt_pk_bf16_f32 v222, v209, v210
	v_cvt_pk_bf16_f32 v223, v211, v212
	global_store_dwordx4 v[216:217], v[220:223], off
	v_lshl_add_u64 v[216:217], v[216:217], 0, s[100:101]
	v_lshlrev_b32_e32 v224, 16, v138
	v_and_b32_e32 v225, 0xffff0000, v138
	v_lshlrev_b32_e32 v226, 16, v139
	v_and_b32_e32 v227, 0xffff0000, v139
	v_lshlrev_b32_e32 v228, 16, v140
	v_and_b32_e32 v229, 0xffff0000, v140
	v_lshlrev_b32_e32 v230, 16, v141
	v_and_b32_e32 v231, 0xffff0000, v141
	v_mul_f32_e32 v224, v52, v224
	v_mul_f32_e32 v225, v52, v225
	v_mul_f32_e32 v226, v52, v226
	v_mul_f32_e32 v227, v52, v227
	v_mul_f32_e32 v228, v52, v228
	v_mul_f32_e32 v229, v52, v229
	v_mul_f32_e32 v230, v52, v230
	v_mul_f32_e32 v231, v52, v231
	v_fma_f32 v205, v205, v20, v224
	v_fma_f32 v206, v206, v20, v225
	v_fma_f32 v207, v207, v20, v226
	v_fma_f32 v208, v208, v20, v227
	v_fma_f32 v209, v209, v20, v228
	v_fma_f32 v210, v210, v20, v229
	v_fma_f32 v211, v211, v20, v230
	v_fma_f32 v212, v212, v20, v231
	s_waitcnt vmcnt(31)
	v_cvt_pk_bf16_f32 v220, v205, v206
	v_cvt_pk_bf16_f32 v221, v207, v208
	v_cvt_pk_bf16_f32 v222, v209, v210
	v_cvt_pk_bf16_f32 v223, v211, v212
	global_store_dwordx4 v[216:217], v[220:223], off
	v_lshl_add_u64 v[216:217], v[216:217], 0, s[100:101]
	v_lshlrev_b32_e32 v224, 16, v142
	v_and_b32_e32 v225, 0xffff0000, v142
	v_lshlrev_b32_e32 v226, 16, v143
	v_and_b32_e32 v227, 0xffff0000, v143
	v_lshlrev_b32_e32 v228, 16, v144
	v_and_b32_e32 v229, 0xffff0000, v144
	v_lshlrev_b32_e32 v230, 16, v145
	v_and_b32_e32 v231, 0xffff0000, v145
	v_mul_f32_e32 v224, v53, v224
	v_mul_f32_e32 v225, v53, v225
	v_mul_f32_e32 v226, v53, v226
	v_mul_f32_e32 v227, v53, v227
	v_mul_f32_e32 v228, v53, v228
	v_mul_f32_e32 v229, v53, v229
	v_mul_f32_e32 v230, v53, v230
	v_mul_f32_e32 v231, v53, v231
	v_fma_f32 v205, v205, v21, v224
	v_fma_f32 v206, v206, v21, v225
	v_fma_f32 v207, v207, v21, v226
	v_fma_f32 v208, v208, v21, v227
	v_fma_f32 v209, v209, v21, v228
	v_fma_f32 v210, v210, v21, v229
	v_fma_f32 v211, v211, v21, v230
	v_fma_f32 v212, v212, v21, v231
	s_waitcnt vmcnt(31)
; __device__ __forceinline__ void phase_scan(bf16_t* Cst, float* nst, const float* gch, const float* mloc, float* mprev) {
;     ...
;                 for (int j = 0; j < 8; ++j) ld[j] = *(const u32x4*)(Cst + ((size_t)(bh * 32 + c0 + j) * 65536 + e8 * 8));
; #pragma unroll
;                 for (int j = 0; j < 8; ++j) { const int c = c0 + j; const float gc = gch[bh * 32 + c], mc = mloc[bh * 32 + c];
;                     const float mn = fmaxf(gc + m, mc), aa = __expf(gc + m - mn), bb = __expf(mc - mn);
;                     float lc[8]; unpack8(ld[j], lc);
;                     *(u32x4*)(Cst + ((size_t)(bh * 32 + c) * 65536 + e8 * 8)) = pack8(st);
; #pragma unroll
;                     for (int e = 0; e < 8; ++e) st[e] = aa * st[e] + bb * lc[e];
	v_cvt_pk_bf16_f32 v220, v205, v206
	v_cvt_pk_bf16_f32 v221, v207, v208
	v_cvt_pk_bf16_f32 v222, v209, v210
	v_cvt_pk_bf16_f32 v223, v211, v212
	global_store_dwordx4 v[216:217], v[220:223], off
	v_lshl_add_u64 v[216:217], v[216:217], 0, s[100:101]
	v_lshlrev_b32_e32 v224, 16, v146
	v_and_b32_e32 v225, 0xffff0000, v146
	v_lshlrev_b32_e32 v226, 16, v147
	v_and_b32_e32 v227, 0xffff0000, v147
	v_lshlrev_b32_e32 v228, 16, v148
	v_and_b32_e32 v229, 0xffff0000, v148
	v_lshlrev_b32_e32 v230, 16, v149
	v_and_b32_e32 v231, 0xffff0000, v149
	v_mul_f32_e32 v224, v54, v224
	v_mul_f32_e32 v225, v54, v225
	v_mul_f32_e32 v226, v54, v226
	v_mul_f32_e32 v227, v54, v227
	v_mul_f32_e32 v228, v54, v228
	v_mul_f32_e32 v229, v54, v229
	v_mul_f32_e32 v230, v54, v230
	v_mul_f32_e32 v231, v54, v231
	v_fma_f32 v205, v205, v22, v224
	v_fma_f32 v206, v206, v22, v225
	v_fma_f32 v207, v207, v22, v226
	v_fma_f32 v208, v208, v22, v227
	v_fma_f32 v209, v209, v22, v228
	v_fma_f32 v210, v210, v22, v229
	v_fma_f32 v211, v211, v22, v230
	v_fma_f32 v212, v212, v22, v231
	s_waitcnt vmcnt(31)
	v_cvt_pk_bf16_f32 v220, v205, v206
	v_cvt_pk_bf16_f32 v221, v207, v208
	v_cvt_pk_bf16_f32 v222, v209, v210
	v_cvt_pk_bf16_f32 v223, v211, v212
	global_store_dwordx4 v[216:217], v[220:223], off
	v_lshl_add_u64 v[216:217], v[216:217], 0, s[100:101]
	v_lshlrev_b32_e32 v224, 16, v150
	v_and_b32_e32 v225, 0xffff0000, v150
	v_lshlrev_b32_e32 v226, 16, v151
	v_and_b32_e32 v227, 0xffff0000, v151
	v_lshlrev_b32_e32 v228, 16, v152
	v_and_b32_e32 v229, 0xffff0000, v152
	v_lshlrev_b32_e32 v230, 16, v153
	v_and_b32_e32 v231, 0xffff0000, v153
	v_mul_f32_e32 v224, v55, v224
	v_mul_f32_e32 v225, v55, v225
	v_mul_f32_e32 v226, v55, v226
	v_mul_f32_e32 v227, v55, v227
	v_mul_f32_e32 v228, v55, v228
	v_mul_f32_e32 v229, v55, v229
	v_mul_f32_e32 v230, v55, v230
	v_mul_f32_e32 v231, v55, v231
	v_fma_f32 v205, v205, v23, v224
	v_fma_f32 v206, v206, v23, v225
	v_fma_f32 v207, v207, v23, v226
	v_fma_f32 v208, v208, v23, v227
	v_fma_f32 v209, v209, v23, v228
	v_fma_f32 v210, v210, v23, v229
	v_fma_f32 v211, v211, v23, v230
	v_fma_f32 v212, v212, v23, v231
	s_waitcnt vmcnt(31)
	v_cvt_pk_bf16_f32 v220, v205, v206
	v_cvt_pk_bf16_f32 v221, v207, v208
	v_cvt_pk_bf16_f32 v222, v209, v210
	v_cvt_pk_bf16_f32 v223, v211, v212
	global_store_dwordx4 v[216:217], v[220:223], off
	v_lshl_add_u64 v[216:217], v[216:217], 0, s[100:101]
	v_lshlrev_b32_e32 v224, 16, v154
	v_and_b32_e32 v225, 0xffff0000, v154
	v_lshlrev_b32_e32 v226, 16, v155
	v_and_b32_e32 v227, 0xffff0000, v155
	v_lshlrev_b32_e32 v228, 16, v156
	v_and_b32_e32 v229, 0xffff0000, v156
	v_lshlrev_b32_e32 v230, 16, v157
	v_and_b32_e32 v231, 0xffff0000, v157
	v_mul_f32_e32 v224, v56, v224
	v_mul_f32_e32 v225, v56, v225
	v_mul_f32_e32 v226, v56, v226
	v_mul_f32_e32 v227, v56, v227
	v_mul_f32_e32 v228, v56, v228
	v_mul_f32_e32 v229, v56, v229
	v_mul_f32_e32 v230, v56, v230
	v_mul_f32_e32 v231, v56, v231
	v_fma_f32 v205, v205, v24, v224
	v_fma_f32 v206, v206, v24, v225
	v_fma_f32 v207, v207, v24, v226
	v_fma_f32 v208, v208, v24, v227
	v_fma_f32 v209, v209, v24, v228
	v_fma_f32 v210, v210, v24, v229
	v_fma_f32 v211, v211, v24, v230
	v_fma_f32 v212, v212, v24, v231
	s_waitcnt vmcnt(31)
	v_cvt_pk_bf16_f32 v220, v205, v206
	v_cvt_pk_bf16_f32 v221, v207, v208
	v_cvt_pk_bf16_f32 v222, v209, v210
	v_cvt_pk_bf16_f32 v223, v211, v212
	global_store_dwordx4 v[216:217], v[220:223], off
	v_lshl_add_u64 v[216:217], v[216:217], 0, s[100:101]
	v_lshlrev_b32_e32 v224, 16, v158
	v_and_b32_e32 v225, 0xffff0000, v158
	v_lshlrev_b32_e32 v226, 16, v159
	v_and_b32_e32 v227, 0xffff0000, v159
	v_lshlrev_b32_e32 v228, 16, v160
	v_and_b32_e32 v229, 0xffff0000, v160
	v_lshlrev_b32_e32 v230, 16, v161
	v_and_b32_e32 v231, 0xffff0000, v161
	v_mul_f32_e32 v224, v57, v224
	v_mul_f32_e32 v225, v57, v225
	v_mul_f32_e32 v226, v57, v226
	v_mul_f32_e32 v227, v57, v227
	v_mul_f32_e32 v228, v57, v228
	v_mul_f32_e32 v229, v57, v229
	v_mul_f32_e32 v230, v57, v230
	v_mul_f32_e32 v231, v57, v231
	v_fma_f32 v205, v205, v25, v224
	v_fma_f32 v206, v206, v25, v225
	v_fma_f32 v207, v207, v25, v226
	v_fma_f32 v208, v208, v25, v227
	v_fma_f32 v209, v209, v25, v228
	v_fma_f32 v210, v210, v25, v229
	v_fma_f32 v211, v211, v25, v230
	v_fma_f32 v212, v212, v25, v231
	s_waitcnt vmcnt(31)
	v_cvt_pk_bf16_f32 v220, v205, v206
	v_cvt_pk_bf16_f32 v221, v207, v208
	v_cvt_pk_bf16_f32 v222, v209, v210
	v_cvt_pk_bf16_f32 v223, v211, v212
	global_store_dwordx4 v[216:217], v[220:223], off
	v_lshl_add_u64 v[216:217], v[216:217], 0, s[100:101]
	v_lshlrev_b32_e32 v224, 16, v162
	v_and_b32_e32 v225, 0xffff0000, v162
	v_lshlrev_b32_e32 v226, 16, v163
	v_and_b32_e32 v227, 0xffff0000, v163
	v_lshlrev_b32_e32 v228, 16, v164
	v_and_b32_e32 v229, 0xffff0000, v164
	v_lshlrev_b32_e32 v230, 16, v165
	v_and_b32_e32 v231, 0xffff0000, v165
	v_mul_f32_e32 v224, v58, v224
	v_mul_f32_e32 v225, v58, v225
	v_mul_f32_e32 v226, v58, v226
	v_mul_f32_e32 v227, v58, v227
	v_mul_f32_e32 v228, v58, v228
	v_mul_f32_e32 v229, v58, v229
	v_mul_f32_e32 v230, v58, v230
	v_mul_f32_e32 v231, v58, v231
	v_fma_f32 v205, v205, v26, v224
	v_fma_f32 v206, v206, v26, v225
	v_fma_f32 v207, v207, v26, v226
	v_fma_f32 v208, v208, v26, v227
	v_fma_f32 v209, v209, v26, v228
	v_fma_f32 v210, v210, v26, v229
	v_fma_f32 v211, v211, v26, v230
	v_fma_f32 v212, v212, v26, v231
	s_waitcnt vmcnt(31)
; __device__ __forceinline__ void phase_scan(bf16_t* Cst, float* nst, const float* gch, const float* mloc, float* mprev) {
;     ...
;                 for (int j = 0; j < 8; ++j) ld[j] = *(const u32x4*)(Cst + ((size_t)(bh * 32 + c0 + j) * 65536 + e8 * 8));
; #pragma unroll
;                 for (int j = 0; j < 8; ++j) { const int c = c0 + j; const float gc = gch[bh * 32 + c], mc = mloc[bh * 32 + c];
;                     const float mn = fmaxf(gc + m, mc), aa = __expf(gc + m - mn), bb = __expf(mc - mn);
;                     float lc[8]; unpack8(ld[j], lc);
;                     *(u32x4*)(Cst + ((size_t)(bh * 32 + c) * 65536 + e8 * 8)) = pack8(st);
; #pragma unroll
;                     for (int e = 0; e < 8; ++e) st[e] = aa * st[e] + bb * lc[e];
	v_cvt_pk_bf16_f32 v220, v205, v206
	v_cvt_pk_bf16_f32 v221, v207, v208
	v_cvt_pk_bf16_f32 v222, v209, v210
	v_cvt_pk_bf16_f32 v223, v211, v212
	global_store_dwordx4 v[216:217], v[220:223], off
	v_lshl_add_u64 v[216:217], v[216:217], 0, s[100:101]
	v_lshlrev_b32_e32 v224, 16, v166
	v_and_b32_e32 v225, 0xffff0000, v166
	v_lshlrev_b32_e32 v226, 16, v167
	v_and_b32_e32 v227, 0xffff0000, v167
	v_lshlrev_b32_e32 v228, 16, v168
	v_and_b32_e32 v229, 0xffff0000, v168
	v_lshlrev_b32_e32 v230, 16, v169
	v_and_b32_e32 v231, 0xffff0000, v169
	v_mul_f32_e32 v224, v59, v224
	v_mul_f32_e32 v225, v59, v225
	v_mul_f32_e32 v226, v59, v226
	v_mul_f32_e32 v227, v59, v227
	v_mul_f32_e32 v228, v59, v228
	v_mul_f32_e32 v229, v59, v229
	v_mul_f32_e32 v230, v59, v230
	v_mul_f32_e32 v231, v59, v231
	v_fma_f32 v205, v205, v27, v224
	v_fma_f32 v206, v206, v27, v225
	v_fma_f32 v207, v207, v27, v226
	v_fma_f32 v208, v208, v27, v227
	v_fma_f32 v209, v209, v27, v228
	v_fma_f32 v210, v210, v27, v229
	v_fma_f32 v211, v211, v27, v230
	v_fma_f32 v212, v212, v27, v231
	s_waitcnt vmcnt(31)
	v_cvt_pk_bf16_f32 v220, v205, v206
	v_cvt_pk_bf16_f32 v221, v207, v208
	v_cvt_pk_bf16_f32 v222, v209, v210
	v_cvt_pk_bf16_f32 v223, v211, v212
	global_store_dwordx4 v[216:217], v[220:223], off
	v_lshl_add_u64 v[216:217], v[216:217], 0, s[100:101]
	v_lshlrev_b32_e32 v224, 16, v170
	v_and_b32_e32 v225, 0xffff0000, v170
	v_lshlrev_b32_e32 v226, 16, v171
	v_and_b32_e32 v227, 0xffff0000, v171
	v_lshlrev_b32_e32 v228, 16, v172
	v_and_b32_e32 v229, 0xffff0000, v172
	v_lshlrev_b32_e32 v230, 16, v173
	v_and_b32_e32 v231, 0xffff0000, v173
	v_mul_f32_e32 v224, v60, v224
	v_mul_f32_e32 v225, v60, v225
	v_mul_f32_e32 v226, v60, v226
	v_mul_f32_e32 v227, v60, v227
	v_mul_f32_e32 v228, v60, v228
	v_mul_f32_e32 v229, v60, v229
	v_mul_f32_e32 v230, v60, v230
	v_mul_f32_e32 v231, v60, v231
	v_fma_f32 v205, v205, v28, v224
	v_fma_f32 v206, v206, v28, v225
	v_fma_f32 v207, v207, v28, v226
	v_fma_f32 v208, v208, v28, v227
	v_fma_f32 v209, v209, v28, v228
	v_fma_f32 v210, v210, v28, v229
	v_fma_f32 v211, v211, v28, v230
	v_fma_f32 v212, v212, v28, v231
	s_waitcnt vmcnt(31)
	v_cvt_pk_bf16_f32 v220, v205, v206
	v_cvt_pk_bf16_f32 v221, v207, v208
	v_cvt_pk_bf16_f32 v222, v209, v210
	v_cvt_pk_bf16_f32 v223, v211, v212
	global_store_dwordx4 v[216:217], v[220:223], off
	v_lshl_add_u64 v[216:217], v[216:217], 0, s[100:101]
	v_lshlrev_b32_e32 v224, 16, v174
	v_and_b32_e32 v225, 0xffff0000, v174
	v_lshlrev_b32_e32 v226, 16, v175
	v_and_b32_e32 v227, 0xffff0000, v175
	v_lshlrev_b32_e32 v228, 16, v176
	v_and_b32_e32 v229, 0xffff0000, v176
	v_lshlrev_b32_e32 v230, 16, v177
	v_and_b32_e32 v231, 0xffff0000, v177
	v_mul_f32_e32 v224, v61, v224
	v_mul_f32_e32 v225, v61, v225
	v_mul_f32_e32 v226, v61, v226
	v_mul_f32_e32 v227, v61, v227
	v_mul_f32_e32 v228, v61, v228
	v_mul_f32_e32 v229, v61, v229
	v_mul_f32_e32 v230, v61, v230
	v_mul_f32_e32 v231, v61, v231
	v_fma_f32 v205, v205, v29, v224
	v_fma_f32 v206, v206, v29, v225
	v_fma_f32 v207, v207, v29, v226
	v_fma_f32 v208, v208, v29, v227
	v_fma_f32 v209, v209, v29, v228
	v_fma_f32 v210, v210, v29, v229
	v_fma_f32 v211, v211, v29, v230
	v_fma_f32 v212, v212, v29, v231
	s_waitcnt vmcnt(31)
	v_cvt_pk_bf16_f32 v220, v205, v206
	v_cvt_pk_bf16_f32 v221, v207, v208
	v_cvt_pk_bf16_f32 v222, v209, v210
	v_cvt_pk_bf16_f32 v223, v211, v212
	global_store_dwordx4 v[216:217], v[220:223], off
	v_lshl_add_u64 v[216:217], v[216:217], 0, s[100:101]
	v_lshlrev_b32_e32 v224, 16, v178
	v_and_b32_e32 v225, 0xffff0000, v178
	v_lshlrev_b32_e32 v226, 16, v179
	v_and_b32_e32 v227, 0xffff0000, v179
	v_lshlrev_b32_e32 v228, 16, v180
	v_and_b32_e32 v229, 0xffff0000, v180
	v_lshlrev_b32_e32 v230, 16, v181
	v_and_b32_e32 v231, 0xffff0000, v181
	v_mul_f32_e32 v224, v62, v224
	v_mul_f32_e32 v225, v62, v225
	v_mul_f32_e32 v226, v62, v226
	v_mul_f32_e32 v227, v62, v227
	v_mul_f32_e32 v228, v62, v228
	v_mul_f32_e32 v229, v62, v229
	v_mul_f32_e32 v230, v62, v230
	v_mul_f32_e32 v231, v62, v231
	v_fma_f32 v205, v205, v30, v224
	v_fma_f32 v206, v206, v30, v225
	v_fma_f32 v207, v207, v30, v226
	v_fma_f32 v208, v208, v30, v227
	v_fma_f32 v209, v209, v30, v228
	v_fma_f32 v210, v210, v30, v229
	v_fma_f32 v211, v211, v30, v230
	v_fma_f32 v212, v212, v30, v231
	s_waitcnt vmcnt(31)
	v_cvt_pk_bf16_f32 v220, v205, v206
	v_cvt_pk_bf16_f32 v221, v207, v208
	v_cvt_pk_bf16_f32 v222, v209, v210
	v_cvt_pk_bf16_f32 v223, v211, v212
	global_store_dwordx4 v[216:217], v[220:223], off
	v_lshl_add_u64 v[216:217], v[216:217], 0, s[100:101]
	v_lshlrev_b32_e32 v224, 16, v182
	v_and_b32_e32 v225, 0xffff0000, v182
	v_lshlrev_b32_e32 v226, 16, v183
	v_and_b32_e32 v227, 0xffff0000, v183
	v_lshlrev_b32_e32 v228, 16, v184
	v_and_b32_e32 v229, 0xffff0000, v184
	v_lshlrev_b32_e32 v230, 16, v185
	v_and_b32_e32 v231, 0xffff0000, v185
	v_mul_f32_e32 v224, v63, v224
	v_mul_f32_e32 v225, v63, v225
	v_mul_f32_e32 v226, v63, v226
	v_mul_f32_e32 v227, v63, v227
	v_mul_f32_e32 v228, v63, v228
	v_mul_f32_e32 v229, v63, v229
	v_mul_f32_e32 v230, v63, v230
	v_mul_f32_e32 v231, v63, v231
	v_fma_f32 v205, v205, v31, v224
	v_fma_f32 v206, v206, v31, v225
	v_fma_f32 v207, v207, v31, v226
	v_fma_f32 v208, v208, v31, v227
	v_fma_f32 v209, v209, v31, v228
	v_fma_f32 v210, v210, v31, v229
	v_fma_f32 v211, v211, v31, v230
	v_fma_f32 v212, v212, v31, v231
	s_waitcnt vmcnt(31)
	v_cvt_pk_bf16_f32 v220, v205, v206
	v_cvt_pk_bf16_f32 v221, v207, v208
	v_cvt_pk_bf16_f32 v222, v209, v210
	v_cvt_pk_bf16_f32 v223, v211, v212
	global_store_dwordx4 v[216:217], v[220:223], off
	v_lshl_add_u64 v[216:217], v[216:217], 0, s[100:101]
	v_lshlrev_b32_e32 v224, 16, v186
	v_and_b32_e32 v225, 0xffff0000, v186
	v_lshlrev_b32_e32 v226, 16, v187
	v_and_b32_e32 v227, 0xffff0000, v187
	v_lshlrev_b32_e32 v228, 16, v188
	v_and_b32_e32 v229, 0xffff0000, v188
	v_lshlrev_b32_e32 v230, 16, v189
	v_and_b32_e32 v231, 0xffff0000, v189
	v_mul_f32_e32 v224, v64, v224
	v_mul_f32_e32 v225, v64, v225
	v_mul_f32_e32 v226, v64, v226
	v_mul_f32_e32 v227, v64, v227
	v_mul_f32_e32 v228, v64, v228
	v_mul_f32_e32 v229, v64, v229
	v_mul_f32_e32 v230, v64, v230
	v_mul_f32_e32 v231, v64, v231
	v_fma_f32 v205, v205, v32, v224
	v_fma_f32 v206, v206, v32, v225
	v_fma_f32 v207, v207, v32, v226
	v_fma_f32 v208, v208, v32, v227
	v_fma_f32 v209, v209, v32, v228
	v_fma_f32 v210, v210, v32, v229
	v_fma_f32 v211, v211, v32, v230
	v_fma_f32 v212, v212, v32, v231
	s_waitcnt vmcnt(31)
	v_cvt_pk_bf16_f32 v220, v205, v206
	v_cvt_pk_bf16_f32 v221, v207, v208
	v_cvt_pk_bf16_f32 v222, v209, v210
	v_cvt_pk_bf16_f32 v223, v211, v212
	global_store_dwordx4 v[216:217], v[220:223], off
	s_branch .LBB0_211
